# final LayerNorm of slabs 0/1: workgroups 0..63 (nine projection tiles next) take no rows at all; waves of workgroups 64..255 take rows w+1536j (10 or 11 each)
# speedup vs baseline: 1.0024x; 1.0024x over previous
.Ltr_28:
	s_branch .LBB0_28
.Ltr_end:
	s_endpgm
.LBB0_336:
	s_waitcnt vmcnt(0)
	s_barrier
	s_and_saveexec_b64 s[0:1], s[90:91]
	v_readlane_b32 s50, v254, 46
	v_readlane_b32 s51, v254, 47
	s_cbranch_execz .LBB0_388
	v_readlane_b32 s4, v254, 32
	s_waitcnt vmcnt(0) expcnt(0) lgkmcnt(0)
	s_nop 0
	v_mov_b32_e32 v0, s4
	ds_read_b32 v2, v0
	v_readlane_b32 s4, v254, 33
	s_waitcnt lgkmcnt(0)
	v_cmp_ne_u32_e32 vcc, 0, v2
	v_mov_b32_e32 v0, s4
	ds_read_b32 v0, v0
	s_cbranch_vccnz .LBB0_352
	s_mov_b32 s10, 1
	s_branch .LBB0_340

.LBB0_745:
	s_or_b64 exec, exec, s[0:1]
	s_mov_b64 s[4:5], s[88:89]
	s_waitcnt lgkmcnt(0)
	s_barrier
	s_cmpk_lg_u32 s56, 0x100
	s_cbranch_scc1 .Llo_generic
	s_load_dwordx2 s[6:7], s[4:5], 0xa0
	s_load_dwordx4 s[40:43], s[4:5], 0x90
	v_mbcnt_lo_u32_b32 v0, -1, 0
	v_mbcnt_hi_u32_b32 v0, -1, v0
	v_lshlrev_b32_e32 v1, 4, v0
	s_lshr_b32 s0, s29, 6
	s_lshl_b32 s96, s92, 24
	s_lshl_b64 s[8:9], s[96:97], 2
	v_mov_b32_e32 v2, 0x3a800000
	v_mov_b32_e32 v4, 0x3727c5ac
	s_waitcnt lgkmcnt(0)
	s_add_u32 s4, s6, s8
	s_addc_u32 s5, s7, s9
	s_cmp_eq_u32 s92, 2
	s_cbranch_scc1 .Llo_even
	s_cmp_lt_u32 s86, 64
	s_cbranch_scc1 .Ltr_29
	s_sub_u32 s1, s86, 64
	s_lshl_b32 s1, s1, 3
	s_add_i32 s0, s0, s1
	s_lshl_b32 s1, s0, 12
	s_add_u32 s4, s4, s1
	s_addc_u32 s5, s5, 0
	s_cmpk_lt_u32 s0, 0x400
	s_cbranch_scc0 .Llo_r10
	global_load_dwordx4 v[40:43], v1, s[4:5]
	global_load_dwordx4 v[44:47], v1, s[4:5] offset:1024
	global_load_dwordx4 v[48:51], v1, s[4:5] offset:2048
	global_load_dwordx4 v[52:55], v1, s[4:5] offset:3072
	global_load_dwordx4 v[8:11], v1, s[40:41]
	global_load_dwordx4 v[12:15], v1, s[40:41] offset:1024
	global_load_dwordx4 v[16:19], v1, s[40:41] offset:2048
	global_load_dwordx4 v[20:23], v1, s[40:41] offset:3072
	global_load_dwordx4 v[24:27], v1, s[42:43]
	global_load_dwordx4 v[28:31], v1, s[42:43] offset:1024
	global_load_dwordx4 v[32:35], v1, s[42:43] offset:2048
	global_load_dwordx4 v[36:39], v1, s[42:43] offset:3072
	v_add_u32_e32 v170, 0x600000, v1
	global_load_dwordx4 v[56:59], v170, s[4:5]
	global_load_dwordx4 v[60:63], v170, s[4:5] offset:1024
	global_load_dwordx4 v[64:67], v170, s[4:5] offset:2048
	global_load_dwordx4 v[68:71], v170, s[4:5] offset:3072
	v_add_u32_e32 v170, 0xc00000, v1
	global_load_dwordx4 v[72:75], v170, s[4:5]
	global_load_dwordx4 v[76:79], v170, s[4:5] offset:1024
	global_load_dwordx4 v[80:83], v170, s[4:5] offset:2048
	global_load_dwordx4 v[84:87], v170, s[4:5] offset:3072
	v_add_u32_e32 v170, 0x1200000, v1
	global_load_dwordx4 v[88:91], v170, s[4:5]
	global_load_dwordx4 v[92:95], v170, s[4:5] offset:1024
	global_load_dwordx4 v[96:99], v170, s[4:5] offset:2048
	global_load_dwordx4 v[100:103], v170, s[4:5] offset:3072
	v_add_u32_e32 v170, 0x1800000, v1
	global_load_dwordx4 v[104:107], v170, s[4:5]
	global_load_dwordx4 v[108:111], v170, s[4:5] offset:1024
	global_load_dwordx4 v[112:115], v170, s[4:5] offset:2048
	global_load_dwordx4 v[116:119], v170, s[4:5] offset:3072
	v_add_u32_e32 v170, 0x1e00000, v1
	global_load_dwordx4 v[120:123], v170, s[4:5]
	global_load_dwordx4 v[124:127], v170, s[4:5] offset:1024
	global_load_dwordx4 v[128:131], v170, s[4:5] offset:2048
	global_load_dwordx4 v[132:135], v170, s[4:5] offset:3072
	v_add_u32_e32 v170, 0x2400000, v1
	global_load_dwordx4 v[136:139], v170, s[4:5]
	global_load_dwordx4 v[140:143], v170, s[4:5] offset:1024
	global_load_dwordx4 v[144:147], v170, s[4:5] offset:2048
	global_load_dwordx4 v[148:151], v170, s[4:5] offset:3072
	v_add_u32_e32 v170, 0x2a00000, v1
	global_load_dwordx4 v[152:155], v170, s[4:5]
	global_load_dwordx4 v[156:159], v170, s[4:5] offset:1024
	global_load_dwordx4 v[160:163], v170, s[4:5] offset:2048
	global_load_dwordx4 v[164:167], v170, s[4:5] offset:3072
	s_waitcnt vmcnt(36)
	v_add_f32_e32 v180, v40, v41
	v_add_f32_e32 v181, v44, v45
	v_add_f32_e32 v182, v48, v49
	v_add_f32_e32 v183, v52, v53
	v_add_f32_e32 v180, v180, v42
	v_add_f32_e32 v181, v181, v46
	v_add_f32_e32 v182, v182, v50
	v_add_f32_e32 v183, v183, v54
	v_add_f32_e32 v180, v180, v43
	v_add_f32_e32 v181, v181, v47
	v_add_f32_e32 v182, v182, v51
	v_add_f32_e32 v183, v183, v55
	v_add_f32_e32 v180, v180, v181
	v_add_f32_e32 v182, v182, v183
	v_add_f32_e32 v180, v180, v182
	s_nop 1
	v_add_f32_dpp v180, v180, v180 quad_perm:[1,0,3,2] row_mask:0xf bank_mask:0xf
	s_nop 1
	v_add_f32_dpp v180, v180, v180 quad_perm:[2,3,0,1] row_mask:0xf bank_mask:0xf
	s_nop 1
	v_add_f32_dpp v180, v180, v180 row_half_mirror row_mask:0xf bank_mask:0xf
	s_nop 1
	v_add_f32_dpp v180, v180, v180 row_mirror row_mask:0xf bank_mask:0xf
	s_nop 1
	v_add_f32_dpp v180, v180, v180 row_bcast:15 row_mask:0xa bank_mask:0xf
	s_nop 1
	v_add_f32_dpp v180, v180, v180 row_bcast:31 row_mask:0xc bank_mask:0xf
	s_nop 0
	v_readlane_b32 s20, v180, 63
	s_nop 1
	v_mul_f32_e32 v184, s20, v2
	v_sub_f32_e32 v40, v40, v184
	v_sub_f32_e32 v41, v41, v184
	v_sub_f32_e32 v42, v42, v184
	v_sub_f32_e32 v43, v43, v184
	v_sub_f32_e32 v44, v44, v184
	v_sub_f32_e32 v45, v45, v184
	v_sub_f32_e32 v46, v46, v184
	v_sub_f32_e32 v47, v47, v184
	v_sub_f32_e32 v48, v48, v184
	v_sub_f32_e32 v49, v49, v184
	v_sub_f32_e32 v50, v50, v184
	v_sub_f32_e32 v51, v51, v184
	v_sub_f32_e32 v52, v52, v184
	v_sub_f32_e32 v53, v53, v184
	v_sub_f32_e32 v54, v54, v184
	v_sub_f32_e32 v55, v55, v184
	v_mul_f32_e32 v180, v40, v40
	v_mul_f32_e32 v181, v44, v44
	v_mul_f32_e32 v182, v48, v48
	v_mul_f32_e32 v183, v52, v52
	v_fmac_f32_e32 v180, v41, v41
	v_fmac_f32_e32 v181, v45, v45
	v_fmac_f32_e32 v182, v49, v49
	v_fmac_f32_e32 v183, v53, v53
	v_fmac_f32_e32 v180, v42, v42
	v_fmac_f32_e32 v181, v46, v46
	v_fmac_f32_e32 v182, v50, v50
	v_fmac_f32_e32 v183, v54, v54
	v_fmac_f32_e32 v180, v43, v43
	v_fmac_f32_e32 v181, v47, v47
	v_fmac_f32_e32 v182, v51, v51
	v_fmac_f32_e32 v183, v55, v55
	v_add_f32_e32 v180, v180, v181
	v_add_f32_e32 v182, v182, v183
	v_add_f32_e32 v180, v180, v182
	s_nop 1
	v_add_f32_dpp v180, v180, v180 quad_perm:[1,0,3,2] row_mask:0xf bank_mask:0xf
	s_nop 1
	v_add_f32_dpp v180, v180, v180 quad_perm:[2,3,0,1] row_mask:0xf bank_mask:0xf
	s_nop 1
	v_add_f32_dpp v180, v180, v180 row_half_mirror row_mask:0xf bank_mask:0xf
	s_nop 1
	v_add_f32_dpp v180, v180, v180 row_mirror row_mask:0xf bank_mask:0xf
	s_nop 1
	v_add_f32_dpp v180, v180, v180 row_bcast:15 row_mask:0xa bank_mask:0xf
	s_nop 1
	v_add_f32_dpp v180, v180, v180 row_bcast:31 row_mask:0xc bank_mask:0xf
	s_nop 0
	v_readlane_b32 s20, v180, 63
	s_nop 1
	v_mov_b32_e32 v185, s20
	v_fma_f32 v185, v185, v2, v4
	v_rsq_f32_e32 v185, v185
	s_nop 0
	v_mul_f32_e32 v40, v40, v185
	v_mul_f32_e32 v41, v41, v185
	v_mul_f32_e32 v42, v42, v185
	v_mul_f32_e32 v43, v43, v185
	v_mul_f32_e32 v44, v44, v185
	v_mul_f32_e32 v45, v45, v185
	v_mul_f32_e32 v46, v46, v185
	v_mul_f32_e32 v47, v47, v185
	v_mul_f32_e32 v48, v48, v185
	v_mul_f32_e32 v49, v49, v185
	v_mul_f32_e32 v50, v50, v185
	v_mul_f32_e32 v51, v51, v185
	v_mul_f32_e32 v52, v52, v185
	v_mul_f32_e32 v53, v53, v185
	v_mul_f32_e32 v54, v54, v185
	v_mul_f32_e32 v55, v55, v185
	s_waitcnt vmcnt(28)
	v_fma_f32 v40, v40, v8, v24
	v_fma_f32 v41, v41, v9, v25
	v_fma_f32 v42, v42, v10, v26
	v_fma_f32 v43, v43, v11, v27
	v_fma_f32 v44, v44, v12, v28
	v_fma_f32 v45, v45, v13, v29
	v_fma_f32 v46, v46, v14, v30
	v_fma_f32 v47, v47, v15, v31
	v_fma_f32 v48, v48, v16, v32
	v_fma_f32 v49, v49, v17, v33
	v_fma_f32 v50, v50, v18, v34
	v_fma_f32 v51, v51, v19, v35
	v_fma_f32 v52, v52, v20, v36
	v_fma_f32 v53, v53, v21, v37
	v_fma_f32 v54, v54, v22, v38
	v_fma_f32 v55, v55, v23, v39
	global_store_dwordx4 v1, v[40:43], s[4:5]
	global_store_dwordx4 v1, v[44:47], s[4:5] offset:1024
	global_store_dwordx4 v1, v[48:51], s[4:5] offset:2048
	global_store_dwordx4 v1, v[52:55], s[4:5] offset:3072
	s_nop 1
	v_add_u32_e32 v170, 0x3000000, v1
	global_load_dwordx4 v[40:43], v170, s[4:5]
	global_load_dwordx4 v[44:47], v170, s[4:5] offset:1024
	global_load_dwordx4 v[48:51], v170, s[4:5] offset:2048
	global_load_dwordx4 v[52:55], v170, s[4:5] offset:3072
	s_waitcnt vmcnt(32)
	v_add_f32_e32 v180, v56, v57
	v_add_f32_e32 v181, v60, v61
	v_add_f32_e32 v182, v64, v65
	v_add_f32_e32 v183, v68, v69
	v_add_f32_e32 v180, v180, v58
	v_add_f32_e32 v181, v181, v62
	v_add_f32_e32 v182, v182, v66
	v_add_f32_e32 v183, v183, v70
	v_add_f32_e32 v180, v180, v59
	v_add_f32_e32 v181, v181, v63
	v_add_f32_e32 v182, v182, v67
	v_add_f32_e32 v183, v183, v71
	v_add_f32_e32 v180, v180, v181
	v_add_f32_e32 v182, v182, v183
	v_add_f32_e32 v180, v180, v182
	s_nop 1
	v_add_f32_dpp v180, v180, v180 quad_perm:[1,0,3,2] row_mask:0xf bank_mask:0xf
	s_nop 1
	v_add_f32_dpp v180, v180, v180 quad_perm:[2,3,0,1] row_mask:0xf bank_mask:0xf
	s_nop 1
	v_add_f32_dpp v180, v180, v180 row_half_mirror row_mask:0xf bank_mask:0xf
	s_nop 1
	v_add_f32_dpp v180, v180, v180 row_mirror row_mask:0xf bank_mask:0xf
	s_nop 1
	v_add_f32_dpp v180, v180, v180 row_bcast:15 row_mask:0xa bank_mask:0xf
	s_nop 1
	v_add_f32_dpp v180, v180, v180 row_bcast:31 row_mask:0xc bank_mask:0xf
	s_nop 0
	v_readlane_b32 s20, v180, 63
	s_nop 1
	v_mul_f32_e32 v184, s20, v2
	v_sub_f32_e32 v56, v56, v184
	v_sub_f32_e32 v57, v57, v184
	v_sub_f32_e32 v58, v58, v184
	v_sub_f32_e32 v59, v59, v184
	v_sub_f32_e32 v60, v60, v184
	v_sub_f32_e32 v61, v61, v184
	v_sub_f32_e32 v62, v62, v184
	v_sub_f32_e32 v63, v63, v184
	v_sub_f32_e32 v64, v64, v184
	v_sub_f32_e32 v65, v65, v184
	v_sub_f32_e32 v66, v66, v184
	v_sub_f32_e32 v67, v67, v184
	v_sub_f32_e32 v68, v68, v184
	v_sub_f32_e32 v69, v69, v184
	v_sub_f32_e32 v70, v70, v184
	v_sub_f32_e32 v71, v71, v184
	v_mul_f32_e32 v180, v56, v56
	v_mul_f32_e32 v181, v60, v60
	v_mul_f32_e32 v182, v64, v64
	v_mul_f32_e32 v183, v68, v68
	v_fmac_f32_e32 v180, v57, v57
	v_fmac_f32_e32 v181, v61, v61
	v_fmac_f32_e32 v182, v65, v65
	v_fmac_f32_e32 v183, v69, v69
	v_fmac_f32_e32 v180, v58, v58
	v_fmac_f32_e32 v181, v62, v62
	v_fmac_f32_e32 v182, v66, v66
	v_fmac_f32_e32 v183, v70, v70
	v_fmac_f32_e32 v180, v59, v59
	v_fmac_f32_e32 v181, v63, v63
	v_fmac_f32_e32 v182, v67, v67
	v_fmac_f32_e32 v183, v71, v71
	v_add_f32_e32 v180, v180, v181
	v_add_f32_e32 v182, v182, v183
	v_add_f32_e32 v180, v180, v182
	s_nop 1
	v_add_f32_dpp v180, v180, v180 quad_perm:[1,0,3,2] row_mask:0xf bank_mask:0xf
	s_nop 1
	v_add_f32_dpp v180, v180, v180 quad_perm:[2,3,0,1] row_mask:0xf bank_mask:0xf
	s_nop 1
	v_add_f32_dpp v180, v180, v180 row_half_mirror row_mask:0xf bank_mask:0xf
	s_nop 1
	v_add_f32_dpp v180, v180, v180 row_mirror row_mask:0xf bank_mask:0xf
	s_nop 1
	v_add_f32_dpp v180, v180, v180 row_bcast:15 row_mask:0xa bank_mask:0xf
	s_nop 1
	v_add_f32_dpp v180, v180, v180 row_bcast:31 row_mask:0xc bank_mask:0xf
	s_nop 0
	v_readlane_b32 s20, v180, 63
	s_nop 1
	v_mov_b32_e32 v185, s20
	v_fma_f32 v185, v185, v2, v4
	v_rsq_f32_e32 v185, v185
	s_nop 0
	v_mul_f32_e32 v56, v56, v185
	v_mul_f32_e32 v57, v57, v185
	v_mul_f32_e32 v58, v58, v185
	v_mul_f32_e32 v59, v59, v185
	v_mul_f32_e32 v60, v60, v185
	v_mul_f32_e32 v61, v61, v185
	v_mul_f32_e32 v62, v62, v185
	v_mul_f32_e32 v63, v63, v185
	v_mul_f32_e32 v64, v64, v185
	v_mul_f32_e32 v65, v65, v185
	v_mul_f32_e32 v66, v66, v185
	v_mul_f32_e32 v67, v67, v185
	v_mul_f32_e32 v68, v68, v185
	v_mul_f32_e32 v69, v69, v185
	v_mul_f32_e32 v70, v70, v185
	v_mul_f32_e32 v71, v71, v185
	v_fma_f32 v56, v56, v8, v24
	v_fma_f32 v57, v57, v9, v25
	v_fma_f32 v58, v58, v10, v26
	v_fma_f32 v59, v59, v11, v27
	v_fma_f32 v60, v60, v12, v28
	v_fma_f32 v61, v61, v13, v29
	v_fma_f32 v62, v62, v14, v30
	v_fma_f32 v63, v63, v15, v31
	v_fma_f32 v64, v64, v16, v32
	v_fma_f32 v65, v65, v17, v33
	v_fma_f32 v66, v66, v18, v34
	v_fma_f32 v67, v67, v19, v35
	v_fma_f32 v68, v68, v20, v36
	v_fma_f32 v69, v69, v21, v37
	v_fma_f32 v70, v70, v22, v38
	v_fma_f32 v71, v71, v23, v39
	v_add_u32_e32 v171, 0x600000, v1
	global_store_dwordx4 v171, v[56:59], s[4:5]
	global_store_dwordx4 v171, v[60:63], s[4:5] offset:1024
	global_store_dwordx4 v171, v[64:67], s[4:5] offset:2048
	global_store_dwordx4 v171, v[68:71], s[4:5] offset:3072
	s_nop 1
	v_add_u32_e32 v170, 0x3600000, v1
	global_load_dwordx4 v[56:59], v170, s[4:5]
	global_load_dwordx4 v[60:63], v170, s[4:5] offset:1024
	global_load_dwordx4 v[64:67], v170, s[4:5] offset:2048
	global_load_dwordx4 v[68:71], v170, s[4:5] offset:3072
	s_waitcnt vmcnt(36)
	v_add_f32_e32 v180, v72, v73
	v_add_f32_e32 v181, v76, v77
	v_add_f32_e32 v182, v80, v81
	v_add_f32_e32 v183, v84, v85
	v_add_f32_e32 v180, v180, v74
	v_add_f32_e32 v181, v181, v78
	v_add_f32_e32 v182, v182, v82
	v_add_f32_e32 v183, v183, v86
	v_add_f32_e32 v180, v180, v75
	v_add_f32_e32 v181, v181, v79
	v_add_f32_e32 v182, v182, v83
	v_add_f32_e32 v183, v183, v87
	v_add_f32_e32 v180, v180, v181
	v_add_f32_e32 v182, v182, v183
	v_add_f32_e32 v180, v180, v182
	s_nop 1
	v_add_f32_dpp v180, v180, v180 quad_perm:[1,0,3,2] row_mask:0xf bank_mask:0xf
	s_nop 1
	v_add_f32_dpp v180, v180, v180 quad_perm:[2,3,0,1] row_mask:0xf bank_mask:0xf
	s_nop 1
	v_add_f32_dpp v180, v180, v180 row_half_mirror row_mask:0xf bank_mask:0xf
	s_nop 1
	v_add_f32_dpp v180, v180, v180 row_mirror row_mask:0xf bank_mask:0xf
	s_nop 1
	v_add_f32_dpp v180, v180, v180 row_bcast:15 row_mask:0xa bank_mask:0xf
	s_nop 1
	v_add_f32_dpp v180, v180, v180 row_bcast:31 row_mask:0xc bank_mask:0xf
	s_nop 0
	v_readlane_b32 s20, v180, 63
	s_nop 1
	v_mul_f32_e32 v184, s20, v2
	v_sub_f32_e32 v72, v72, v184
	v_sub_f32_e32 v73, v73, v184
	v_sub_f32_e32 v74, v74, v184
	v_sub_f32_e32 v75, v75, v184
	v_sub_f32_e32 v76, v76, v184
	v_sub_f32_e32 v77, v77, v184
	v_sub_f32_e32 v78, v78, v184
	v_sub_f32_e32 v79, v79, v184
	v_sub_f32_e32 v80, v80, v184
	v_sub_f32_e32 v81, v81, v184
	v_sub_f32_e32 v82, v82, v184
	v_sub_f32_e32 v83, v83, v184
	v_sub_f32_e32 v84, v84, v184
	v_sub_f32_e32 v85, v85, v184
	v_sub_f32_e32 v86, v86, v184
	v_sub_f32_e32 v87, v87, v184
	v_mul_f32_e32 v180, v72, v72
	v_mul_f32_e32 v181, v76, v76
	v_mul_f32_e32 v182, v80, v80
	v_mul_f32_e32 v183, v84, v84
	v_fmac_f32_e32 v180, v73, v73
	v_fmac_f32_e32 v181, v77, v77
	v_fmac_f32_e32 v182, v81, v81
	v_fmac_f32_e32 v183, v85, v85
	v_fmac_f32_e32 v180, v74, v74
	v_fmac_f32_e32 v181, v78, v78
	v_fmac_f32_e32 v182, v82, v82
	v_fmac_f32_e32 v183, v86, v86
	v_fmac_f32_e32 v180, v75, v75
	v_fmac_f32_e32 v181, v79, v79
	v_fmac_f32_e32 v182, v83, v83
	v_fmac_f32_e32 v183, v87, v87
	v_add_f32_e32 v180, v180, v181
	v_add_f32_e32 v182, v182, v183
	v_add_f32_e32 v180, v180, v182
	s_nop 1
	v_add_f32_dpp v180, v180, v180 quad_perm:[1,0,3,2] row_mask:0xf bank_mask:0xf
	s_nop 1
	v_add_f32_dpp v180, v180, v180 quad_perm:[2,3,0,1] row_mask:0xf bank_mask:0xf
	s_nop 1
	v_add_f32_dpp v180, v180, v180 row_half_mirror row_mask:0xf bank_mask:0xf
	s_nop 1
	v_add_f32_dpp v180, v180, v180 row_mirror row_mask:0xf bank_mask:0xf
	s_nop 1
	v_add_f32_dpp v180, v180, v180 row_bcast:15 row_mask:0xa bank_mask:0xf
	s_nop 1
	v_add_f32_dpp v180, v180, v180 row_bcast:31 row_mask:0xc bank_mask:0xf
	s_nop 0
	v_readlane_b32 s20, v180, 63
	s_nop 1
	v_mov_b32_e32 v185, s20
	v_fma_f32 v185, v185, v2, v4
	v_rsq_f32_e32 v185, v185
	s_nop 0
	v_mul_f32_e32 v72, v72, v185
	v_mul_f32_e32 v73, v73, v185
	v_mul_f32_e32 v74, v74, v185
	v_mul_f32_e32 v75, v75, v185
	v_mul_f32_e32 v76, v76, v185
	v_mul_f32_e32 v77, v77, v185
	v_mul_f32_e32 v78, v78, v185
	v_mul_f32_e32 v79, v79, v185
	v_mul_f32_e32 v80, v80, v185
	v_mul_f32_e32 v81, v81, v185
	v_mul_f32_e32 v82, v82, v185
	v_mul_f32_e32 v83, v83, v185
	v_mul_f32_e32 v84, v84, v185
	v_mul_f32_e32 v85, v85, v185
	v_mul_f32_e32 v86, v86, v185
	v_mul_f32_e32 v87, v87, v185
	v_fma_f32 v72, v72, v8, v24
	v_fma_f32 v73, v73, v9, v25
	v_fma_f32 v74, v74, v10, v26
	v_fma_f32 v75, v75, v11, v27
	v_fma_f32 v76, v76, v12, v28
	v_fma_f32 v77, v77, v13, v29
	v_fma_f32 v78, v78, v14, v30
	v_fma_f32 v79, v79, v15, v31
	v_fma_f32 v80, v80, v16, v32
	v_fma_f32 v81, v81, v17, v33
	v_fma_f32 v82, v82, v18, v34
	v_fma_f32 v83, v83, v19, v35
	v_fma_f32 v84, v84, v20, v36
	v_fma_f32 v85, v85, v21, v37
	v_fma_f32 v86, v86, v22, v38
	v_fma_f32 v87, v87, v23, v39
	v_add_u32_e32 v171, 0xc00000, v1
	global_store_dwordx4 v171, v[72:75], s[4:5]
	global_store_dwordx4 v171, v[76:79], s[4:5] offset:1024
	global_store_dwordx4 v171, v[80:83], s[4:5] offset:2048
	global_store_dwordx4 v171, v[84:87], s[4:5] offset:3072
	s_nop 1
	v_add_u32_e32 v170, 0x3c00000, v1
	global_load_dwordx4 v[72:75], v170, s[4:5]
	global_load_dwordx4 v[76:79], v170, s[4:5] offset:1024
	global_load_dwordx4 v[80:83], v170, s[4:5] offset:2048
	global_load_dwordx4 v[84:87], v170, s[4:5] offset:3072
	s_waitcnt vmcnt(40)
	v_add_f32_e32 v180, v88, v89
	v_add_f32_e32 v181, v92, v93
	v_add_f32_e32 v182, v96, v97
	v_add_f32_e32 v183, v100, v101
	v_add_f32_e32 v180, v180, v90
	v_add_f32_e32 v181, v181, v94
	v_add_f32_e32 v182, v182, v98
	v_add_f32_e32 v183, v183, v102
	v_add_f32_e32 v180, v180, v91
	v_add_f32_e32 v181, v181, v95
	v_add_f32_e32 v182, v182, v99
	v_add_f32_e32 v183, v183, v103
	v_add_f32_e32 v180, v180, v181
	v_add_f32_e32 v182, v182, v183
	v_add_f32_e32 v180, v180, v182
	s_nop 1
	v_add_f32_dpp v180, v180, v180 quad_perm:[1,0,3,2] row_mask:0xf bank_mask:0xf
	s_nop 1
	v_add_f32_dpp v180, v180, v180 quad_perm:[2,3,0,1] row_mask:0xf bank_mask:0xf
	s_nop 1
	v_add_f32_dpp v180, v180, v180 row_half_mirror row_mask:0xf bank_mask:0xf
	s_nop 1
	v_add_f32_dpp v180, v180, v180 row_mirror row_mask:0xf bank_mask:0xf
	s_nop 1
	v_add_f32_dpp v180, v180, v180 row_bcast:15 row_mask:0xa bank_mask:0xf
	s_nop 1
	v_add_f32_dpp v180, v180, v180 row_bcast:31 row_mask:0xc bank_mask:0xf
	s_nop 0
	v_readlane_b32 s20, v180, 63
	s_nop 1
	v_mul_f32_e32 v184, s20, v2
	v_sub_f32_e32 v88, v88, v184
	v_sub_f32_e32 v89, v89, v184
	v_sub_f32_e32 v90, v90, v184
	v_sub_f32_e32 v91, v91, v184
	v_sub_f32_e32 v92, v92, v184
	v_sub_f32_e32 v93, v93, v184
	v_sub_f32_e32 v94, v94, v184
	v_sub_f32_e32 v95, v95, v184
	v_sub_f32_e32 v96, v96, v184
	v_sub_f32_e32 v97, v97, v184
	v_sub_f32_e32 v98, v98, v184
	v_sub_f32_e32 v99, v99, v184
	v_sub_f32_e32 v100, v100, v184
	v_sub_f32_e32 v101, v101, v184
	v_sub_f32_e32 v102, v102, v184
	v_sub_f32_e32 v103, v103, v184
	v_mul_f32_e32 v180, v88, v88
	v_mul_f32_e32 v181, v92, v92
	v_mul_f32_e32 v182, v96, v96
	v_mul_f32_e32 v183, v100, v100
	v_fmac_f32_e32 v180, v89, v89
	v_fmac_f32_e32 v181, v93, v93
	v_fmac_f32_e32 v182, v97, v97
	v_fmac_f32_e32 v183, v101, v101
	v_fmac_f32_e32 v180, v90, v90
	v_fmac_f32_e32 v181, v94, v94
	v_fmac_f32_e32 v182, v98, v98
	v_fmac_f32_e32 v183, v102, v102
	v_fmac_f32_e32 v180, v91, v91
	v_fmac_f32_e32 v181, v95, v95
	v_fmac_f32_e32 v182, v99, v99
	v_fmac_f32_e32 v183, v103, v103
	v_add_f32_e32 v180, v180, v181
	v_add_f32_e32 v182, v182, v183
	v_add_f32_e32 v180, v180, v182
	s_nop 1
	v_add_f32_dpp v180, v180, v180 quad_perm:[1,0,3,2] row_mask:0xf bank_mask:0xf
	s_nop 1
	v_add_f32_dpp v180, v180, v180 quad_perm:[2,3,0,1] row_mask:0xf bank_mask:0xf
	s_nop 1
	v_add_f32_dpp v180, v180, v180 row_half_mirror row_mask:0xf bank_mask:0xf
	s_nop 1
	v_add_f32_dpp v180, v180, v180 row_mirror row_mask:0xf bank_mask:0xf
	s_nop 1
	v_add_f32_dpp v180, v180, v180 row_bcast:15 row_mask:0xa bank_mask:0xf
	s_nop 1
	v_add_f32_dpp v180, v180, v180 row_bcast:31 row_mask:0xc bank_mask:0xf
	s_nop 0
	v_readlane_b32 s20, v180, 63
	s_nop 1
	v_mov_b32_e32 v185, s20
	v_fma_f32 v185, v185, v2, v4
	v_rsq_f32_e32 v185, v185
	s_nop 0
	v_mul_f32_e32 v88, v88, v185
	v_mul_f32_e32 v89, v89, v185
	v_mul_f32_e32 v90, v90, v185
	v_mul_f32_e32 v91, v91, v185
	v_mul_f32_e32 v92, v92, v185
	v_mul_f32_e32 v93, v93, v185
	v_mul_f32_e32 v94, v94, v185
	v_mul_f32_e32 v95, v95, v185
	v_mul_f32_e32 v96, v96, v185
	v_mul_f32_e32 v97, v97, v185
	v_mul_f32_e32 v98, v98, v185
	v_mul_f32_e32 v99, v99, v185
	v_mul_f32_e32 v100, v100, v185
	v_mul_f32_e32 v101, v101, v185
	v_mul_f32_e32 v102, v102, v185
	v_mul_f32_e32 v103, v103, v185
	v_fma_f32 v88, v88, v8, v24
	v_fma_f32 v89, v89, v9, v25
	v_fma_f32 v90, v90, v10, v26
	v_fma_f32 v91, v91, v11, v27
	v_fma_f32 v92, v92, v12, v28
	v_fma_f32 v93, v93, v13, v29
	v_fma_f32 v94, v94, v14, v30
	v_fma_f32 v95, v95, v15, v31
	v_fma_f32 v96, v96, v16, v32
	v_fma_f32 v97, v97, v17, v33
	v_fma_f32 v98, v98, v18, v34
	v_fma_f32 v99, v99, v19, v35
	v_fma_f32 v100, v100, v20, v36
	v_fma_f32 v101, v101, v21, v37
	v_fma_f32 v102, v102, v22, v38
	v_fma_f32 v103, v103, v23, v39
	v_add_u32_e32 v171, 0x1200000, v1
	global_store_dwordx4 v171, v[88:91], s[4:5]
	global_store_dwordx4 v171, v[92:95], s[4:5] offset:1024
	global_store_dwordx4 v171, v[96:99], s[4:5] offset:2048
	global_store_dwordx4 v171, v[100:103], s[4:5] offset:3072
	s_waitcnt vmcnt(40)
	v_add_f32_e32 v180, v104, v105
	v_add_f32_e32 v181, v108, v109
	v_add_f32_e32 v182, v112, v113
	v_add_f32_e32 v183, v116, v117
	v_add_f32_e32 v180, v180, v106
	v_add_f32_e32 v181, v181, v110
	v_add_f32_e32 v182, v182, v114
	v_add_f32_e32 v183, v183, v118
	v_add_f32_e32 v180, v180, v107
	v_add_f32_e32 v181, v181, v111
	v_add_f32_e32 v182, v182, v115
	v_add_f32_e32 v183, v183, v119
	v_add_f32_e32 v180, v180, v181
	v_add_f32_e32 v182, v182, v183
	v_add_f32_e32 v180, v180, v182
	s_nop 1
	v_add_f32_dpp v180, v180, v180 quad_perm:[1,0,3,2] row_mask:0xf bank_mask:0xf
	s_nop 1
	v_add_f32_dpp v180, v180, v180 quad_perm:[2,3,0,1] row_mask:0xf bank_mask:0xf
	s_nop 1
	v_add_f32_dpp v180, v180, v180 row_half_mirror row_mask:0xf bank_mask:0xf
	s_nop 1
	v_add_f32_dpp v180, v180, v180 row_mirror row_mask:0xf bank_mask:0xf
	s_nop 1
	v_add_f32_dpp v180, v180, v180 row_bcast:15 row_mask:0xa bank_mask:0xf
	s_nop 1
	v_add_f32_dpp v180, v180, v180 row_bcast:31 row_mask:0xc bank_mask:0xf
	s_nop 0
	v_readlane_b32 s20, v180, 63
	s_nop 1
	v_mul_f32_e32 v184, s20, v2
	v_sub_f32_e32 v104, v104, v184
	v_sub_f32_e32 v105, v105, v184
	v_sub_f32_e32 v106, v106, v184
	v_sub_f32_e32 v107, v107, v184
	v_sub_f32_e32 v108, v108, v184
	v_sub_f32_e32 v109, v109, v184
	v_sub_f32_e32 v110, v110, v184
	v_sub_f32_e32 v111, v111, v184
	v_sub_f32_e32 v112, v112, v184
	v_sub_f32_e32 v113, v113, v184
	v_sub_f32_e32 v114, v114, v184
	v_sub_f32_e32 v115, v115, v184
	v_sub_f32_e32 v116, v116, v184
	v_sub_f32_e32 v117, v117, v184
	v_sub_f32_e32 v118, v118, v184
	v_sub_f32_e32 v119, v119, v184
	v_mul_f32_e32 v180, v104, v104
	v_mul_f32_e32 v181, v108, v108
	v_mul_f32_e32 v182, v112, v112
	v_mul_f32_e32 v183, v116, v116
	v_fmac_f32_e32 v180, v105, v105
	v_fmac_f32_e32 v181, v109, v109
	v_fmac_f32_e32 v182, v113, v113
	v_fmac_f32_e32 v183, v117, v117
	v_fmac_f32_e32 v180, v106, v106
	v_fmac_f32_e32 v181, v110, v110
	v_fmac_f32_e32 v182, v114, v114
	v_fmac_f32_e32 v183, v118, v118
	v_fmac_f32_e32 v180, v107, v107
	v_fmac_f32_e32 v181, v111, v111
	v_fmac_f32_e32 v182, v115, v115
	v_fmac_f32_e32 v183, v119, v119
	v_add_f32_e32 v180, v180, v181
	v_add_f32_e32 v182, v182, v183
	v_add_f32_e32 v180, v180, v182
	s_nop 1
	v_add_f32_dpp v180, v180, v180 quad_perm:[1,0,3,2] row_mask:0xf bank_mask:0xf
	s_nop 1
	v_add_f32_dpp v180, v180, v180 quad_perm:[2,3,0,1] row_mask:0xf bank_mask:0xf
	s_nop 1
	v_add_f32_dpp v180, v180, v180 row_half_mirror row_mask:0xf bank_mask:0xf
	s_nop 1
	v_add_f32_dpp v180, v180, v180 row_mirror row_mask:0xf bank_mask:0xf
	s_nop 1
	v_add_f32_dpp v180, v180, v180 row_bcast:15 row_mask:0xa bank_mask:0xf
	s_nop 1
	v_add_f32_dpp v180, v180, v180 row_bcast:31 row_mask:0xc bank_mask:0xf
	s_nop 0
	v_readlane_b32 s20, v180, 63
	s_nop 1
	v_mov_b32_e32 v185, s20
	v_fma_f32 v185, v185, v2, v4
	v_rsq_f32_e32 v185, v185
	s_nop 0
	v_mul_f32_e32 v104, v104, v185
	v_mul_f32_e32 v105, v105, v185
	v_mul_f32_e32 v106, v106, v185
	v_mul_f32_e32 v107, v107, v185
	v_mul_f32_e32 v108, v108, v185
	v_mul_f32_e32 v109, v109, v185
	v_mul_f32_e32 v110, v110, v185
	v_mul_f32_e32 v111, v111, v185
	v_mul_f32_e32 v112, v112, v185
	v_mul_f32_e32 v113, v113, v185
	v_mul_f32_e32 v114, v114, v185
	v_mul_f32_e32 v115, v115, v185
	v_mul_f32_e32 v116, v116, v185
	v_mul_f32_e32 v117, v117, v185
	v_mul_f32_e32 v118, v118, v185
	v_mul_f32_e32 v119, v119, v185
	v_fma_f32 v104, v104, v8, v24
	v_fma_f32 v105, v105, v9, v25
	v_fma_f32 v106, v106, v10, v26
	v_fma_f32 v107, v107, v11, v27
	v_fma_f32 v108, v108, v12, v28
	v_fma_f32 v109, v109, v13, v29
	v_fma_f32 v110, v110, v14, v30
	v_fma_f32 v111, v111, v15, v31
	v_fma_f32 v112, v112, v16, v32
	v_fma_f32 v113, v113, v17, v33
	v_fma_f32 v114, v114, v18, v34
	v_fma_f32 v115, v115, v19, v35
	v_fma_f32 v116, v116, v20, v36
	v_fma_f32 v117, v117, v21, v37
	v_fma_f32 v118, v118, v22, v38
	v_fma_f32 v119, v119, v23, v39
	v_add_u32_e32 v171, 0x1800000, v1
	global_store_dwordx4 v171, v[104:107], s[4:5]
	global_store_dwordx4 v171, v[108:111], s[4:5] offset:1024
	global_store_dwordx4 v171, v[112:115], s[4:5] offset:2048
	global_store_dwordx4 v171, v[116:119], s[4:5] offset:3072
	s_waitcnt vmcnt(40)
	v_add_f32_e32 v180, v120, v121
	v_add_f32_e32 v181, v124, v125
	v_add_f32_e32 v182, v128, v129
	v_add_f32_e32 v183, v132, v133
	v_add_f32_e32 v180, v180, v122
	v_add_f32_e32 v181, v181, v126
	v_add_f32_e32 v182, v182, v130
	v_add_f32_e32 v183, v183, v134
	v_add_f32_e32 v180, v180, v123
	v_add_f32_e32 v181, v181, v127
	v_add_f32_e32 v182, v182, v131
	v_add_f32_e32 v183, v183, v135
	v_add_f32_e32 v180, v180, v181
	v_add_f32_e32 v182, v182, v183
	v_add_f32_e32 v180, v180, v182
	s_nop 1
	v_add_f32_dpp v180, v180, v180 quad_perm:[1,0,3,2] row_mask:0xf bank_mask:0xf
	s_nop 1
	v_add_f32_dpp v180, v180, v180 quad_perm:[2,3,0,1] row_mask:0xf bank_mask:0xf
	s_nop 1
	v_add_f32_dpp v180, v180, v180 row_half_mirror row_mask:0xf bank_mask:0xf
	s_nop 1
	v_add_f32_dpp v180, v180, v180 row_mirror row_mask:0xf bank_mask:0xf
	s_nop 1
	v_add_f32_dpp v180, v180, v180 row_bcast:15 row_mask:0xa bank_mask:0xf
	s_nop 1
	v_add_f32_dpp v180, v180, v180 row_bcast:31 row_mask:0xc bank_mask:0xf
	s_nop 0
	v_readlane_b32 s20, v180, 63
	s_nop 1
	v_mul_f32_e32 v184, s20, v2
	v_sub_f32_e32 v120, v120, v184
	v_sub_f32_e32 v121, v121, v184
	v_sub_f32_e32 v122, v122, v184
	v_sub_f32_e32 v123, v123, v184
	v_sub_f32_e32 v124, v124, v184
	v_sub_f32_e32 v125, v125, v184
	v_sub_f32_e32 v126, v126, v184
	v_sub_f32_e32 v127, v127, v184
	v_sub_f32_e32 v128, v128, v184
	v_sub_f32_e32 v129, v129, v184
	v_sub_f32_e32 v130, v130, v184
	v_sub_f32_e32 v131, v131, v184
	v_sub_f32_e32 v132, v132, v184
	v_sub_f32_e32 v133, v133, v184
	v_sub_f32_e32 v134, v134, v184
	v_sub_f32_e32 v135, v135, v184
	v_mul_f32_e32 v180, v120, v120
	v_mul_f32_e32 v181, v124, v124
	v_mul_f32_e32 v182, v128, v128
	v_mul_f32_e32 v183, v132, v132
	v_fmac_f32_e32 v180, v121, v121
	v_fmac_f32_e32 v181, v125, v125
	v_fmac_f32_e32 v182, v129, v129
	v_fmac_f32_e32 v183, v133, v133
	v_fmac_f32_e32 v180, v122, v122
	v_fmac_f32_e32 v181, v126, v126
	v_fmac_f32_e32 v182, v130, v130
	v_fmac_f32_e32 v183, v134, v134
	v_fmac_f32_e32 v180, v123, v123
	v_fmac_f32_e32 v181, v127, v127
	v_fmac_f32_e32 v182, v131, v131
	v_fmac_f32_e32 v183, v135, v135
	v_add_f32_e32 v180, v180, v181
	v_add_f32_e32 v182, v182, v183
	v_add_f32_e32 v180, v180, v182
	s_nop 1
	v_add_f32_dpp v180, v180, v180 quad_perm:[1,0,3,2] row_mask:0xf bank_mask:0xf
	s_nop 1
	v_add_f32_dpp v180, v180, v180 quad_perm:[2,3,0,1] row_mask:0xf bank_mask:0xf
	s_nop 1
	v_add_f32_dpp v180, v180, v180 row_half_mirror row_mask:0xf bank_mask:0xf
	s_nop 1
	v_add_f32_dpp v180, v180, v180 row_mirror row_mask:0xf bank_mask:0xf
	s_nop 1
	v_add_f32_dpp v180, v180, v180 row_bcast:15 row_mask:0xa bank_mask:0xf
	s_nop 1
	v_add_f32_dpp v180, v180, v180 row_bcast:31 row_mask:0xc bank_mask:0xf
	s_nop 0
	v_readlane_b32 s20, v180, 63
	s_nop 1
	v_mov_b32_e32 v185, s20
	v_fma_f32 v185, v185, v2, v4
	v_rsq_f32_e32 v185, v185
	s_nop 0
	v_mul_f32_e32 v120, v120, v185
	v_mul_f32_e32 v121, v121, v185
	v_mul_f32_e32 v122, v122, v185
	v_mul_f32_e32 v123, v123, v185
	v_mul_f32_e32 v124, v124, v185
	v_mul_f32_e32 v125, v125, v185
	v_mul_f32_e32 v126, v126, v185
	v_mul_f32_e32 v127, v127, v185
	v_mul_f32_e32 v128, v128, v185
	v_mul_f32_e32 v129, v129, v185
	v_mul_f32_e32 v130, v130, v185
	v_mul_f32_e32 v131, v131, v185
	v_mul_f32_e32 v132, v132, v185
	v_mul_f32_e32 v133, v133, v185
	v_mul_f32_e32 v134, v134, v185
	v_mul_f32_e32 v135, v135, v185
	v_fma_f32 v120, v120, v8, v24
	v_fma_f32 v121, v121, v9, v25
	v_fma_f32 v122, v122, v10, v26
	v_fma_f32 v123, v123, v11, v27
	v_fma_f32 v124, v124, v12, v28
	v_fma_f32 v125, v125, v13, v29
	v_fma_f32 v126, v126, v14, v30
	v_fma_f32 v127, v127, v15, v31
	v_fma_f32 v128, v128, v16, v32
	v_fma_f32 v129, v129, v17, v33
	v_fma_f32 v130, v130, v18, v34
	v_fma_f32 v131, v131, v19, v35
	v_fma_f32 v132, v132, v20, v36
	v_fma_f32 v133, v133, v21, v37
	v_fma_f32 v134, v134, v22, v38
	v_fma_f32 v135, v135, v23, v39
	v_add_u32_e32 v171, 0x1e00000, v1
	global_store_dwordx4 v171, v[120:123], s[4:5]
	global_store_dwordx4 v171, v[124:127], s[4:5] offset:1024
	global_store_dwordx4 v171, v[128:131], s[4:5] offset:2048
	global_store_dwordx4 v171, v[132:135], s[4:5] offset:3072
	s_waitcnt vmcnt(40)
	v_add_f32_e32 v180, v136, v137
	v_add_f32_e32 v181, v140, v141
	v_add_f32_e32 v182, v144, v145
	v_add_f32_e32 v183, v148, v149
	v_add_f32_e32 v180, v180, v138
	v_add_f32_e32 v181, v181, v142
	v_add_f32_e32 v182, v182, v146
	v_add_f32_e32 v183, v183, v150
	v_add_f32_e32 v180, v180, v139
	v_add_f32_e32 v181, v181, v143
	v_add_f32_e32 v182, v182, v147
	v_add_f32_e32 v183, v183, v151
	v_add_f32_e32 v180, v180, v181
	v_add_f32_e32 v182, v182, v183
	v_add_f32_e32 v180, v180, v182
	s_nop 1
	v_add_f32_dpp v180, v180, v180 quad_perm:[1,0,3,2] row_mask:0xf bank_mask:0xf
	s_nop 1
	v_add_f32_dpp v180, v180, v180 quad_perm:[2,3,0,1] row_mask:0xf bank_mask:0xf
	s_nop 1
	v_add_f32_dpp v180, v180, v180 row_half_mirror row_mask:0xf bank_mask:0xf
	s_nop 1
	v_add_f32_dpp v180, v180, v180 row_mirror row_mask:0xf bank_mask:0xf
	s_nop 1
	v_add_f32_dpp v180, v180, v180 row_bcast:15 row_mask:0xa bank_mask:0xf
	s_nop 1
	v_add_f32_dpp v180, v180, v180 row_bcast:31 row_mask:0xc bank_mask:0xf
	s_nop 0
	v_readlane_b32 s20, v180, 63
	s_nop 1
	v_mul_f32_e32 v184, s20, v2
	v_sub_f32_e32 v136, v136, v184
	v_sub_f32_e32 v137, v137, v184
	v_sub_f32_e32 v138, v138, v184
	v_sub_f32_e32 v139, v139, v184
	v_sub_f32_e32 v140, v140, v184
	v_sub_f32_e32 v141, v141, v184
	v_sub_f32_e32 v142, v142, v184
	v_sub_f32_e32 v143, v143, v184
	v_sub_f32_e32 v144, v144, v184
	v_sub_f32_e32 v145, v145, v184
	v_sub_f32_e32 v146, v146, v184
	v_sub_f32_e32 v147, v147, v184
	v_sub_f32_e32 v148, v148, v184
	v_sub_f32_e32 v149, v149, v184
	v_sub_f32_e32 v150, v150, v184
	v_sub_f32_e32 v151, v151, v184
	v_mul_f32_e32 v180, v136, v136
	v_mul_f32_e32 v181, v140, v140
	v_mul_f32_e32 v182, v144, v144
	v_mul_f32_e32 v183, v148, v148
	v_fmac_f32_e32 v180, v137, v137
	v_fmac_f32_e32 v181, v141, v141
	v_fmac_f32_e32 v182, v145, v145
	v_fmac_f32_e32 v183, v149, v149
	v_fmac_f32_e32 v180, v138, v138
	v_fmac_f32_e32 v181, v142, v142
	v_fmac_f32_e32 v182, v146, v146
	v_fmac_f32_e32 v183, v150, v150
	v_fmac_f32_e32 v180, v139, v139
	v_fmac_f32_e32 v181, v143, v143
	v_fmac_f32_e32 v182, v147, v147
	v_fmac_f32_e32 v183, v151, v151
	v_add_f32_e32 v180, v180, v181
	v_add_f32_e32 v182, v182, v183
	v_add_f32_e32 v180, v180, v182
	s_nop 1
	v_add_f32_dpp v180, v180, v180 quad_perm:[1,0,3,2] row_mask:0xf bank_mask:0xf
	s_nop 1
	v_add_f32_dpp v180, v180, v180 quad_perm:[2,3,0,1] row_mask:0xf bank_mask:0xf
	s_nop 1
	v_add_f32_dpp v180, v180, v180 row_half_mirror row_mask:0xf bank_mask:0xf
	s_nop 1
	v_add_f32_dpp v180, v180, v180 row_mirror row_mask:0xf bank_mask:0xf
	s_nop 1
	v_add_f32_dpp v180, v180, v180 row_bcast:15 row_mask:0xa bank_mask:0xf
	s_nop 1
	v_add_f32_dpp v180, v180, v180 row_bcast:31 row_mask:0xc bank_mask:0xf
	s_nop 0
	v_readlane_b32 s20, v180, 63
	s_nop 1
	v_mov_b32_e32 v185, s20
	v_fma_f32 v185, v185, v2, v4
	v_rsq_f32_e32 v185, v185
	s_nop 0
	v_mul_f32_e32 v136, v136, v185
	v_mul_f32_e32 v137, v137, v185
	v_mul_f32_e32 v138, v138, v185
	v_mul_f32_e32 v139, v139, v185
	v_mul_f32_e32 v140, v140, v185
	v_mul_f32_e32 v141, v141, v185
	v_mul_f32_e32 v142, v142, v185
	v_mul_f32_e32 v143, v143, v185
	v_mul_f32_e32 v144, v144, v185
	v_mul_f32_e32 v145, v145, v185
	v_mul_f32_e32 v146, v146, v185
	v_mul_f32_e32 v147, v147, v185
	v_mul_f32_e32 v148, v148, v185
	v_mul_f32_e32 v149, v149, v185
	v_mul_f32_e32 v150, v150, v185
	v_mul_f32_e32 v151, v151, v185
	v_fma_f32 v136, v136, v8, v24
	v_fma_f32 v137, v137, v9, v25
	v_fma_f32 v138, v138, v10, v26
	v_fma_f32 v139, v139, v11, v27
	v_fma_f32 v140, v140, v12, v28
	v_fma_f32 v141, v141, v13, v29
	v_fma_f32 v142, v142, v14, v30
	v_fma_f32 v143, v143, v15, v31
	v_fma_f32 v144, v144, v16, v32
	v_fma_f32 v145, v145, v17, v33
	v_fma_f32 v146, v146, v18, v34
	v_fma_f32 v147, v147, v19, v35
	v_fma_f32 v148, v148, v20, v36
	v_fma_f32 v149, v149, v21, v37
	v_fma_f32 v150, v150, v22, v38
	v_fma_f32 v151, v151, v23, v39
	v_add_u32_e32 v171, 0x2400000, v1
	global_store_dwordx4 v171, v[136:139], s[4:5]
	global_store_dwordx4 v171, v[140:143], s[4:5] offset:1024
	global_store_dwordx4 v171, v[144:147], s[4:5] offset:2048
	global_store_dwordx4 v171, v[148:151], s[4:5] offset:3072
	s_waitcnt vmcnt(40)
	v_add_f32_e32 v180, v152, v153
	v_add_f32_e32 v181, v156, v157
	v_add_f32_e32 v182, v160, v161
	v_add_f32_e32 v183, v164, v165
	v_add_f32_e32 v180, v180, v154
	v_add_f32_e32 v181, v181, v158
	v_add_f32_e32 v182, v182, v162
	v_add_f32_e32 v183, v183, v166
	v_add_f32_e32 v180, v180, v155
	v_add_f32_e32 v181, v181, v159
	v_add_f32_e32 v182, v182, v163
	v_add_f32_e32 v183, v183, v167
	v_add_f32_e32 v180, v180, v181
	v_add_f32_e32 v182, v182, v183
	v_add_f32_e32 v180, v180, v182
	s_nop 1
	v_add_f32_dpp v180, v180, v180 quad_perm:[1,0,3,2] row_mask:0xf bank_mask:0xf
	s_nop 1
	v_add_f32_dpp v180, v180, v180 quad_perm:[2,3,0,1] row_mask:0xf bank_mask:0xf
	s_nop 1
	v_add_f32_dpp v180, v180, v180 row_half_mirror row_mask:0xf bank_mask:0xf
	s_nop 1
	v_add_f32_dpp v180, v180, v180 row_mirror row_mask:0xf bank_mask:0xf
	s_nop 1
	v_add_f32_dpp v180, v180, v180 row_bcast:15 row_mask:0xa bank_mask:0xf
	s_nop 1
	v_add_f32_dpp v180, v180, v180 row_bcast:31 row_mask:0xc bank_mask:0xf
	s_nop 0
	v_readlane_b32 s20, v180, 63
	s_nop 1
	v_mul_f32_e32 v184, s20, v2
	v_sub_f32_e32 v152, v152, v184
	v_sub_f32_e32 v153, v153, v184
	v_sub_f32_e32 v154, v154, v184
	v_sub_f32_e32 v155, v155, v184
	v_sub_f32_e32 v156, v156, v184
	v_sub_f32_e32 v157, v157, v184
	v_sub_f32_e32 v158, v158, v184
	v_sub_f32_e32 v159, v159, v184
	v_sub_f32_e32 v160, v160, v184
	v_sub_f32_e32 v161, v161, v184
	v_sub_f32_e32 v162, v162, v184
	v_sub_f32_e32 v163, v163, v184
	v_sub_f32_e32 v164, v164, v184
	v_sub_f32_e32 v165, v165, v184
	v_sub_f32_e32 v166, v166, v184
	v_sub_f32_e32 v167, v167, v184
	v_mul_f32_e32 v180, v152, v152
	v_mul_f32_e32 v181, v156, v156
	v_mul_f32_e32 v182, v160, v160
	v_mul_f32_e32 v183, v164, v164
	v_fmac_f32_e32 v180, v153, v153
	v_fmac_f32_e32 v181, v157, v157
	v_fmac_f32_e32 v182, v161, v161
	v_fmac_f32_e32 v183, v165, v165
	v_fmac_f32_e32 v180, v154, v154
	v_fmac_f32_e32 v181, v158, v158
	v_fmac_f32_e32 v182, v162, v162
	v_fmac_f32_e32 v183, v166, v166
	v_fmac_f32_e32 v180, v155, v155
	v_fmac_f32_e32 v181, v159, v159
	v_fmac_f32_e32 v182, v163, v163
	v_fmac_f32_e32 v183, v167, v167
	v_add_f32_e32 v180, v180, v181
	v_add_f32_e32 v182, v182, v183
	v_add_f32_e32 v180, v180, v182
	s_nop 1
	v_add_f32_dpp v180, v180, v180 quad_perm:[1,0,3,2] row_mask:0xf bank_mask:0xf
	s_nop 1
	v_add_f32_dpp v180, v180, v180 quad_perm:[2,3,0,1] row_mask:0xf bank_mask:0xf
	s_nop 1
	v_add_f32_dpp v180, v180, v180 row_half_mirror row_mask:0xf bank_mask:0xf
	s_nop 1
	v_add_f32_dpp v180, v180, v180 row_mirror row_mask:0xf bank_mask:0xf
	s_nop 1
	v_add_f32_dpp v180, v180, v180 row_bcast:15 row_mask:0xa bank_mask:0xf
	s_nop 1
	v_add_f32_dpp v180, v180, v180 row_bcast:31 row_mask:0xc bank_mask:0xf
	s_nop 0
	v_readlane_b32 s20, v180, 63
	s_nop 1
	v_mov_b32_e32 v185, s20
	v_fma_f32 v185, v185, v2, v4
	v_rsq_f32_e32 v185, v185
	s_nop 0
	v_mul_f32_e32 v152, v152, v185
	v_mul_f32_e32 v153, v153, v185
	v_mul_f32_e32 v154, v154, v185
	v_mul_f32_e32 v155, v155, v185
	v_mul_f32_e32 v156, v156, v185
	v_mul_f32_e32 v157, v157, v185
	v_mul_f32_e32 v158, v158, v185
	v_mul_f32_e32 v159, v159, v185
	v_mul_f32_e32 v160, v160, v185
	v_mul_f32_e32 v161, v161, v185
	v_mul_f32_e32 v162, v162, v185
	v_mul_f32_e32 v163, v163, v185
	v_mul_f32_e32 v164, v164, v185
	v_mul_f32_e32 v165, v165, v185
	v_mul_f32_e32 v166, v166, v185
	v_mul_f32_e32 v167, v167, v185
	v_fma_f32 v152, v152, v8, v24
	v_fma_f32 v153, v153, v9, v25
	v_fma_f32 v154, v154, v10, v26
	v_fma_f32 v155, v155, v11, v27
	v_fma_f32 v156, v156, v12, v28
	v_fma_f32 v157, v157, v13, v29
	v_fma_f32 v158, v158, v14, v30
	v_fma_f32 v159, v159, v15, v31
	v_fma_f32 v160, v160, v16, v32
	v_fma_f32 v161, v161, v17, v33
	v_fma_f32 v162, v162, v18, v34
	v_fma_f32 v163, v163, v19, v35
	v_fma_f32 v164, v164, v20, v36
	v_fma_f32 v165, v165, v21, v37
	v_fma_f32 v166, v166, v22, v38
	v_fma_f32 v167, v167, v23, v39
	v_add_u32_e32 v171, 0x2a00000, v1
	global_store_dwordx4 v171, v[152:155], s[4:5]
	global_store_dwordx4 v171, v[156:159], s[4:5] offset:1024
	global_store_dwordx4 v171, v[160:163], s[4:5] offset:2048
	global_store_dwordx4 v171, v[164:167], s[4:5] offset:3072
	s_waitcnt vmcnt(36)
	v_add_f32_e32 v180, v40, v41
	v_add_f32_e32 v181, v44, v45
	v_add_f32_e32 v182, v48, v49
	v_add_f32_e32 v183, v52, v53
	v_add_f32_e32 v180, v180, v42
	v_add_f32_e32 v181, v181, v46
	v_add_f32_e32 v182, v182, v50
	v_add_f32_e32 v183, v183, v54
	v_add_f32_e32 v180, v180, v43
	v_add_f32_e32 v181, v181, v47
	v_add_f32_e32 v182, v182, v51
	v_add_f32_e32 v183, v183, v55
	v_add_f32_e32 v180, v180, v181
	v_add_f32_e32 v182, v182, v183
	v_add_f32_e32 v180, v180, v182
	s_nop 1
	v_add_f32_dpp v180, v180, v180 quad_perm:[1,0,3,2] row_mask:0xf bank_mask:0xf
	s_nop 1
	v_add_f32_dpp v180, v180, v180 quad_perm:[2,3,0,1] row_mask:0xf bank_mask:0xf
	s_nop 1
	v_add_f32_dpp v180, v180, v180 row_half_mirror row_mask:0xf bank_mask:0xf
	s_nop 1
	v_add_f32_dpp v180, v180, v180 row_mirror row_mask:0xf bank_mask:0xf
	s_nop 1
	v_add_f32_dpp v180, v180, v180 row_bcast:15 row_mask:0xa bank_mask:0xf
	s_nop 1
	v_add_f32_dpp v180, v180, v180 row_bcast:31 row_mask:0xc bank_mask:0xf
	s_nop 0
	v_readlane_b32 s20, v180, 63
	s_nop 1
	v_mul_f32_e32 v184, s20, v2
	v_sub_f32_e32 v40, v40, v184
	v_sub_f32_e32 v41, v41, v184
	v_sub_f32_e32 v42, v42, v184
	v_sub_f32_e32 v43, v43, v184
	v_sub_f32_e32 v44, v44, v184
	v_sub_f32_e32 v45, v45, v184
	v_sub_f32_e32 v46, v46, v184
	v_sub_f32_e32 v47, v47, v184
	v_sub_f32_e32 v48, v48, v184
	v_sub_f32_e32 v49, v49, v184
	v_sub_f32_e32 v50, v50, v184
	v_sub_f32_e32 v51, v51, v184
	v_sub_f32_e32 v52, v52, v184
	v_sub_f32_e32 v53, v53, v184
	v_sub_f32_e32 v54, v54, v184
	v_sub_f32_e32 v55, v55, v184
	v_mul_f32_e32 v180, v40, v40
	v_mul_f32_e32 v181, v44, v44
	v_mul_f32_e32 v182, v48, v48
	v_mul_f32_e32 v183, v52, v52
	v_fmac_f32_e32 v180, v41, v41
	v_fmac_f32_e32 v181, v45, v45
	v_fmac_f32_e32 v182, v49, v49
	v_fmac_f32_e32 v183, v53, v53
	v_fmac_f32_e32 v180, v42, v42
	v_fmac_f32_e32 v181, v46, v46
	v_fmac_f32_e32 v182, v50, v50
	v_fmac_f32_e32 v183, v54, v54
	v_fmac_f32_e32 v180, v43, v43
	v_fmac_f32_e32 v181, v47, v47
	v_fmac_f32_e32 v182, v51, v51
	v_fmac_f32_e32 v183, v55, v55
	v_add_f32_e32 v180, v180, v181
	v_add_f32_e32 v182, v182, v183
	v_add_f32_e32 v180, v180, v182
	s_nop 1
	v_add_f32_dpp v180, v180, v180 quad_perm:[1,0,3,2] row_mask:0xf bank_mask:0xf
	s_nop 1
	v_add_f32_dpp v180, v180, v180 quad_perm:[2,3,0,1] row_mask:0xf bank_mask:0xf
	s_nop 1
	v_add_f32_dpp v180, v180, v180 row_half_mirror row_mask:0xf bank_mask:0xf
	s_nop 1
	v_add_f32_dpp v180, v180, v180 row_mirror row_mask:0xf bank_mask:0xf
	s_nop 1
	v_add_f32_dpp v180, v180, v180 row_bcast:15 row_mask:0xa bank_mask:0xf
	s_nop 1
	v_add_f32_dpp v180, v180, v180 row_bcast:31 row_mask:0xc bank_mask:0xf
	s_nop 0
	v_readlane_b32 s20, v180, 63
	s_nop 1
	v_mov_b32_e32 v185, s20
	v_fma_f32 v185, v185, v2, v4
	v_rsq_f32_e32 v185, v185
	s_nop 0
	v_mul_f32_e32 v40, v40, v185
	v_mul_f32_e32 v41, v41, v185
	v_mul_f32_e32 v42, v42, v185
	v_mul_f32_e32 v43, v43, v185
	v_mul_f32_e32 v44, v44, v185
	v_mul_f32_e32 v45, v45, v185
	v_mul_f32_e32 v46, v46, v185
	v_mul_f32_e32 v47, v47, v185
	v_mul_f32_e32 v48, v48, v185
	v_mul_f32_e32 v49, v49, v185
	v_mul_f32_e32 v50, v50, v185
	v_mul_f32_e32 v51, v51, v185
	v_mul_f32_e32 v52, v52, v185
	v_mul_f32_e32 v53, v53, v185
	v_mul_f32_e32 v54, v54, v185
	v_mul_f32_e32 v55, v55, v185
	v_fma_f32 v40, v40, v8, v24
	v_fma_f32 v41, v41, v9, v25
	v_fma_f32 v42, v42, v10, v26
	v_fma_f32 v43, v43, v11, v27
	v_fma_f32 v44, v44, v12, v28
	v_fma_f32 v45, v45, v13, v29
	v_fma_f32 v46, v46, v14, v30
	v_fma_f32 v47, v47, v15, v31
	v_fma_f32 v48, v48, v16, v32
	v_fma_f32 v49, v49, v17, v33
	v_fma_f32 v50, v50, v18, v34
	v_fma_f32 v51, v51, v19, v35
	v_fma_f32 v52, v52, v20, v36
	v_fma_f32 v53, v53, v21, v37
	v_fma_f32 v54, v54, v22, v38
	v_fma_f32 v55, v55, v23, v39
	v_add_u32_e32 v171, 0x3000000, v1
	global_store_dwordx4 v171, v[40:43], s[4:5]
	global_store_dwordx4 v171, v[44:47], s[4:5] offset:1024
	global_store_dwordx4 v171, v[48:51], s[4:5] offset:2048
	global_store_dwordx4 v171, v[52:55], s[4:5] offset:3072
	s_waitcnt vmcnt(32)
	v_add_f32_e32 v180, v56, v57
	v_add_f32_e32 v181, v60, v61
	v_add_f32_e32 v182, v64, v65
	v_add_f32_e32 v183, v68, v69
	v_add_f32_e32 v180, v180, v58
	v_add_f32_e32 v181, v181, v62
	v_add_f32_e32 v182, v182, v66
	v_add_f32_e32 v183, v183, v70
	v_add_f32_e32 v180, v180, v59
	v_add_f32_e32 v181, v181, v63
	v_add_f32_e32 v182, v182, v67
	v_add_f32_e32 v183, v183, v71
	v_add_f32_e32 v180, v180, v181
	v_add_f32_e32 v182, v182, v183
	v_add_f32_e32 v180, v180, v182
	s_nop 1
	v_add_f32_dpp v180, v180, v180 quad_perm:[1,0,3,2] row_mask:0xf bank_mask:0xf
	s_nop 1
	v_add_f32_dpp v180, v180, v180 quad_perm:[2,3,0,1] row_mask:0xf bank_mask:0xf
	s_nop 1
	v_add_f32_dpp v180, v180, v180 row_half_mirror row_mask:0xf bank_mask:0xf
	s_nop 1
	v_add_f32_dpp v180, v180, v180 row_mirror row_mask:0xf bank_mask:0xf
	s_nop 1
	v_add_f32_dpp v180, v180, v180 row_bcast:15 row_mask:0xa bank_mask:0xf
	s_nop 1
	v_add_f32_dpp v180, v180, v180 row_bcast:31 row_mask:0xc bank_mask:0xf
	s_nop 0
	v_readlane_b32 s20, v180, 63
	s_nop 1
	v_mul_f32_e32 v184, s20, v2
	v_sub_f32_e32 v56, v56, v184
	v_sub_f32_e32 v57, v57, v184
	v_sub_f32_e32 v58, v58, v184
	v_sub_f32_e32 v59, v59, v184
	v_sub_f32_e32 v60, v60, v184
	v_sub_f32_e32 v61, v61, v184
	v_sub_f32_e32 v62, v62, v184
	v_sub_f32_e32 v63, v63, v184
	v_sub_f32_e32 v64, v64, v184
	v_sub_f32_e32 v65, v65, v184
	v_sub_f32_e32 v66, v66, v184
	v_sub_f32_e32 v67, v67, v184
	v_sub_f32_e32 v68, v68, v184
	v_sub_f32_e32 v69, v69, v184
	v_sub_f32_e32 v70, v70, v184
	v_sub_f32_e32 v71, v71, v184
	v_mul_f32_e32 v180, v56, v56
	v_mul_f32_e32 v181, v60, v60
	v_mul_f32_e32 v182, v64, v64
	v_mul_f32_e32 v183, v68, v68
	v_fmac_f32_e32 v180, v57, v57
	v_fmac_f32_e32 v181, v61, v61
	v_fmac_f32_e32 v182, v65, v65
	v_fmac_f32_e32 v183, v69, v69
	v_fmac_f32_e32 v180, v58, v58
	v_fmac_f32_e32 v181, v62, v62
	v_fmac_f32_e32 v182, v66, v66
	v_fmac_f32_e32 v183, v70, v70
	v_fmac_f32_e32 v180, v59, v59
	v_fmac_f32_e32 v181, v63, v63
	v_fmac_f32_e32 v182, v67, v67
	v_fmac_f32_e32 v183, v71, v71
	v_add_f32_e32 v180, v180, v181
	v_add_f32_e32 v182, v182, v183
	v_add_f32_e32 v180, v180, v182
	s_nop 1
	v_add_f32_dpp v180, v180, v180 quad_perm:[1,0,3,2] row_mask:0xf bank_mask:0xf
	s_nop 1
	v_add_f32_dpp v180, v180, v180 quad_perm:[2,3,0,1] row_mask:0xf bank_mask:0xf
	s_nop 1
	v_add_f32_dpp v180, v180, v180 row_half_mirror row_mask:0xf bank_mask:0xf
	s_nop 1
	v_add_f32_dpp v180, v180, v180 row_mirror row_mask:0xf bank_mask:0xf
	s_nop 1
	v_add_f32_dpp v180, v180, v180 row_bcast:15 row_mask:0xa bank_mask:0xf
	s_nop 1
	v_add_f32_dpp v180, v180, v180 row_bcast:31 row_mask:0xc bank_mask:0xf
	s_nop 0
	v_readlane_b32 s20, v180, 63
	s_nop 1
	v_mov_b32_e32 v185, s20
	v_fma_f32 v185, v185, v2, v4
	v_rsq_f32_e32 v185, v185
	s_nop 0
	v_mul_f32_e32 v56, v56, v185
	v_mul_f32_e32 v57, v57, v185
	v_mul_f32_e32 v58, v58, v185
	v_mul_f32_e32 v59, v59, v185
	v_mul_f32_e32 v60, v60, v185
	v_mul_f32_e32 v61, v61, v185
	v_mul_f32_e32 v62, v62, v185
	v_mul_f32_e32 v63, v63, v185
	v_mul_f32_e32 v64, v64, v185
	v_mul_f32_e32 v65, v65, v185
	v_mul_f32_e32 v66, v66, v185
	v_mul_f32_e32 v67, v67, v185
	v_mul_f32_e32 v68, v68, v185
	v_mul_f32_e32 v69, v69, v185
	v_mul_f32_e32 v70, v70, v185
	v_mul_f32_e32 v71, v71, v185
	v_fma_f32 v56, v56, v8, v24
	v_fma_f32 v57, v57, v9, v25
	v_fma_f32 v58, v58, v10, v26
	v_fma_f32 v59, v59, v11, v27
	v_fma_f32 v60, v60, v12, v28
	v_fma_f32 v61, v61, v13, v29
	v_fma_f32 v62, v62, v14, v30
	v_fma_f32 v63, v63, v15, v31
	v_fma_f32 v64, v64, v16, v32
	v_fma_f32 v65, v65, v17, v33
	v_fma_f32 v66, v66, v18, v34
	v_fma_f32 v67, v67, v19, v35
	v_fma_f32 v68, v68, v20, v36
	v_fma_f32 v69, v69, v21, v37
	v_fma_f32 v70, v70, v22, v38
	v_fma_f32 v71, v71, v23, v39
	v_add_u32_e32 v171, 0x3600000, v1
	global_store_dwordx4 v171, v[56:59], s[4:5]
	global_store_dwordx4 v171, v[60:63], s[4:5] offset:1024
	global_store_dwordx4 v171, v[64:67], s[4:5] offset:2048
	global_store_dwordx4 v171, v[68:71], s[4:5] offset:3072
	s_waitcnt vmcnt(28)
	v_add_f32_e32 v180, v72, v73
	v_add_f32_e32 v181, v76, v77
	v_add_f32_e32 v182, v80, v81
	v_add_f32_e32 v183, v84, v85
	v_add_f32_e32 v180, v180, v74
	v_add_f32_e32 v181, v181, v78
	v_add_f32_e32 v182, v182, v82
	v_add_f32_e32 v183, v183, v86
	v_add_f32_e32 v180, v180, v75
	v_add_f32_e32 v181, v181, v79
	v_add_f32_e32 v182, v182, v83
	v_add_f32_e32 v183, v183, v87
	v_add_f32_e32 v180, v180, v181
	v_add_f32_e32 v182, v182, v183
	v_add_f32_e32 v180, v180, v182
	s_nop 1
	v_add_f32_dpp v180, v180, v180 quad_perm:[1,0,3,2] row_mask:0xf bank_mask:0xf
	s_nop 1
	v_add_f32_dpp v180, v180, v180 quad_perm:[2,3,0,1] row_mask:0xf bank_mask:0xf
	s_nop 1
	v_add_f32_dpp v180, v180, v180 row_half_mirror row_mask:0xf bank_mask:0xf
	s_nop 1
	v_add_f32_dpp v180, v180, v180 row_mirror row_mask:0xf bank_mask:0xf
	s_nop 1
	v_add_f32_dpp v180, v180, v180 row_bcast:15 row_mask:0xa bank_mask:0xf
	s_nop 1
	v_add_f32_dpp v180, v180, v180 row_bcast:31 row_mask:0xc bank_mask:0xf
	s_nop 0
	v_readlane_b32 s20, v180, 63
	s_nop 1
	v_mul_f32_e32 v184, s20, v2
	v_sub_f32_e32 v72, v72, v184
	v_sub_f32_e32 v73, v73, v184
	v_sub_f32_e32 v74, v74, v184
	v_sub_f32_e32 v75, v75, v184
	v_sub_f32_e32 v76, v76, v184
	v_sub_f32_e32 v77, v77, v184
	v_sub_f32_e32 v78, v78, v184
	v_sub_f32_e32 v79, v79, v184
	v_sub_f32_e32 v80, v80, v184
	v_sub_f32_e32 v81, v81, v184
	v_sub_f32_e32 v82, v82, v184
	v_sub_f32_e32 v83, v83, v184
	v_sub_f32_e32 v84, v84, v184
	v_sub_f32_e32 v85, v85, v184
	v_sub_f32_e32 v86, v86, v184
	v_sub_f32_e32 v87, v87, v184
	v_mul_f32_e32 v180, v72, v72
	v_mul_f32_e32 v181, v76, v76
	v_mul_f32_e32 v182, v80, v80
	v_mul_f32_e32 v183, v84, v84
	v_fmac_f32_e32 v180, v73, v73
	v_fmac_f32_e32 v181, v77, v77
	v_fmac_f32_e32 v182, v81, v81
	v_fmac_f32_e32 v183, v85, v85
	v_fmac_f32_e32 v180, v74, v74
	v_fmac_f32_e32 v181, v78, v78
	v_fmac_f32_e32 v182, v82, v82
	v_fmac_f32_e32 v183, v86, v86
	v_fmac_f32_e32 v180, v75, v75
	v_fmac_f32_e32 v181, v79, v79
	v_fmac_f32_e32 v182, v83, v83
	v_fmac_f32_e32 v183, v87, v87
	v_add_f32_e32 v180, v180, v181
	v_add_f32_e32 v182, v182, v183
	v_add_f32_e32 v180, v180, v182
	s_nop 1
	v_add_f32_dpp v180, v180, v180 quad_perm:[1,0,3,2] row_mask:0xf bank_mask:0xf
	s_nop 1
	v_add_f32_dpp v180, v180, v180 quad_perm:[2,3,0,1] row_mask:0xf bank_mask:0xf
	s_nop 1
	v_add_f32_dpp v180, v180, v180 row_half_mirror row_mask:0xf bank_mask:0xf
	s_nop 1
	v_add_f32_dpp v180, v180, v180 row_mirror row_mask:0xf bank_mask:0xf
	s_nop 1
	v_add_f32_dpp v180, v180, v180 row_bcast:15 row_mask:0xa bank_mask:0xf
	s_nop 1
	v_add_f32_dpp v180, v180, v180 row_bcast:31 row_mask:0xc bank_mask:0xf
	s_nop 0
	v_readlane_b32 s20, v180, 63
	s_nop 1
	v_mov_b32_e32 v185, s20
	v_fma_f32 v185, v185, v2, v4
	v_rsq_f32_e32 v185, v185
	s_nop 0
	v_mul_f32_e32 v72, v72, v185
	v_mul_f32_e32 v73, v73, v185
	v_mul_f32_e32 v74, v74, v185
	v_mul_f32_e32 v75, v75, v185
	v_mul_f32_e32 v76, v76, v185
	v_mul_f32_e32 v77, v77, v185
	v_mul_f32_e32 v78, v78, v185
	v_mul_f32_e32 v79, v79, v185
	v_mul_f32_e32 v80, v80, v185
	v_mul_f32_e32 v81, v81, v185
	v_mul_f32_e32 v82, v82, v185
	v_mul_f32_e32 v83, v83, v185
	v_mul_f32_e32 v84, v84, v185
	v_mul_f32_e32 v85, v85, v185
	v_mul_f32_e32 v86, v86, v185
	v_mul_f32_e32 v87, v87, v185
	v_fma_f32 v72, v72, v8, v24
	v_fma_f32 v73, v73, v9, v25
	v_fma_f32 v74, v74, v10, v26
	v_fma_f32 v75, v75, v11, v27
	v_fma_f32 v76, v76, v12, v28
	v_fma_f32 v77, v77, v13, v29
	v_fma_f32 v78, v78, v14, v30
	v_fma_f32 v79, v79, v15, v31
	v_fma_f32 v80, v80, v16, v32
	v_fma_f32 v81, v81, v17, v33
	v_fma_f32 v82, v82, v18, v34
	v_fma_f32 v83, v83, v19, v35
	v_fma_f32 v84, v84, v20, v36
	v_fma_f32 v85, v85, v21, v37
	v_fma_f32 v86, v86, v22, v38
	v_fma_f32 v87, v87, v23, v39
	v_add_u32_e32 v171, 0x3c00000, v1
	global_store_dwordx4 v171, v[72:75], s[4:5]
	global_store_dwordx4 v171, v[76:79], s[4:5] offset:1024
	global_store_dwordx4 v171, v[80:83], s[4:5] offset:2048
	global_store_dwordx4 v171, v[84:87], s[4:5] offset:3072
	s_branch .Ltr_29
.Llo_r10:
	global_load_dwordx4 v[40:43], v1, s[4:5]
	global_load_dwordx4 v[44:47], v1, s[4:5] offset:1024
	global_load_dwordx4 v[48:51], v1, s[4:5] offset:2048
	global_load_dwordx4 v[52:55], v1, s[4:5] offset:3072
	global_load_dwordx4 v[8:11], v1, s[40:41]
	global_load_dwordx4 v[12:15], v1, s[40:41] offset:1024
	global_load_dwordx4 v[16:19], v1, s[40:41] offset:2048
	global_load_dwordx4 v[20:23], v1, s[40:41] offset:3072
	global_load_dwordx4 v[24:27], v1, s[42:43]
	global_load_dwordx4 v[28:31], v1, s[42:43] offset:1024
	global_load_dwordx4 v[32:35], v1, s[42:43] offset:2048
	global_load_dwordx4 v[36:39], v1, s[42:43] offset:3072
	v_add_u32_e32 v170, 0x600000, v1
	global_load_dwordx4 v[56:59], v170, s[4:5]
	global_load_dwordx4 v[60:63], v170, s[4:5] offset:1024
	global_load_dwordx4 v[64:67], v170, s[4:5] offset:2048
	global_load_dwordx4 v[68:71], v170, s[4:5] offset:3072
	v_add_u32_e32 v170, 0xc00000, v1
	global_load_dwordx4 v[72:75], v170, s[4:5]
	global_load_dwordx4 v[76:79], v170, s[4:5] offset:1024
	global_load_dwordx4 v[80:83], v170, s[4:5] offset:2048
	global_load_dwordx4 v[84:87], v170, s[4:5] offset:3072
	v_add_u32_e32 v170, 0x1200000, v1
	global_load_dwordx4 v[88:91], v170, s[4:5]
	global_load_dwordx4 v[92:95], v170, s[4:5] offset:1024
	global_load_dwordx4 v[96:99], v170, s[4:5] offset:2048
	global_load_dwordx4 v[100:103], v170, s[4:5] offset:3072
	v_add_u32_e32 v170, 0x1800000, v1
	global_load_dwordx4 v[104:107], v170, s[4:5]
	global_load_dwordx4 v[108:111], v170, s[4:5] offset:1024
	global_load_dwordx4 v[112:115], v170, s[4:5] offset:2048
	global_load_dwordx4 v[116:119], v170, s[4:5] offset:3072
	v_add_u32_e32 v170, 0x1e00000, v1
	global_load_dwordx4 v[120:123], v170, s[4:5]
	global_load_dwordx4 v[124:127], v170, s[4:5] offset:1024
	global_load_dwordx4 v[128:131], v170, s[4:5] offset:2048
	global_load_dwordx4 v[132:135], v170, s[4:5] offset:3072
	v_add_u32_e32 v170, 0x2400000, v1
	global_load_dwordx4 v[136:139], v170, s[4:5]
	global_load_dwordx4 v[140:143], v170, s[4:5] offset:1024
	global_load_dwordx4 v[144:147], v170, s[4:5] offset:2048
	global_load_dwordx4 v[148:151], v170, s[4:5] offset:3072
	v_add_u32_e32 v170, 0x2a00000, v1
	global_load_dwordx4 v[152:155], v170, s[4:5]
	global_load_dwordx4 v[156:159], v170, s[4:5] offset:1024
	global_load_dwordx4 v[160:163], v170, s[4:5] offset:2048
	global_load_dwordx4 v[164:167], v170, s[4:5] offset:3072
	s_waitcnt vmcnt(36)
	v_add_f32_e32 v180, v40, v41
	v_add_f32_e32 v181, v44, v45
	v_add_f32_e32 v182, v48, v49
	v_add_f32_e32 v183, v52, v53
	v_add_f32_e32 v180, v180, v42
	v_add_f32_e32 v181, v181, v46
	v_add_f32_e32 v182, v182, v50
	v_add_f32_e32 v183, v183, v54
	v_add_f32_e32 v180, v180, v43
	v_add_f32_e32 v181, v181, v47
	v_add_f32_e32 v182, v182, v51
	v_add_f32_e32 v183, v183, v55
	v_add_f32_e32 v180, v180, v181
	v_add_f32_e32 v182, v182, v183
	v_add_f32_e32 v180, v180, v182
	s_nop 1
	v_add_f32_dpp v180, v180, v180 quad_perm:[1,0,3,2] row_mask:0xf bank_mask:0xf
	s_nop 1
	v_add_f32_dpp v180, v180, v180 quad_perm:[2,3,0,1] row_mask:0xf bank_mask:0xf
	s_nop 1
	v_add_f32_dpp v180, v180, v180 row_half_mirror row_mask:0xf bank_mask:0xf
	s_nop 1
	v_add_f32_dpp v180, v180, v180 row_mirror row_mask:0xf bank_mask:0xf
	s_nop 1
	v_add_f32_dpp v180, v180, v180 row_bcast:15 row_mask:0xa bank_mask:0xf
	s_nop 1
	v_add_f32_dpp v180, v180, v180 row_bcast:31 row_mask:0xc bank_mask:0xf
	s_nop 0
	v_readlane_b32 s20, v180, 63
	s_nop 1
	v_mul_f32_e32 v184, s20, v2
	v_sub_f32_e32 v40, v40, v184
	v_sub_f32_e32 v41, v41, v184
	v_sub_f32_e32 v42, v42, v184
	v_sub_f32_e32 v43, v43, v184
	v_sub_f32_e32 v44, v44, v184
	v_sub_f32_e32 v45, v45, v184
	v_sub_f32_e32 v46, v46, v184
	v_sub_f32_e32 v47, v47, v184
	v_sub_f32_e32 v48, v48, v184
	v_sub_f32_e32 v49, v49, v184
	v_sub_f32_e32 v50, v50, v184
	v_sub_f32_e32 v51, v51, v184
	v_sub_f32_e32 v52, v52, v184
	v_sub_f32_e32 v53, v53, v184
	v_sub_f32_e32 v54, v54, v184
	v_sub_f32_e32 v55, v55, v184
	v_mul_f32_e32 v180, v40, v40
	v_mul_f32_e32 v181, v44, v44
	v_mul_f32_e32 v182, v48, v48
	v_mul_f32_e32 v183, v52, v52
	v_fmac_f32_e32 v180, v41, v41
	v_fmac_f32_e32 v181, v45, v45
	v_fmac_f32_e32 v182, v49, v49
	v_fmac_f32_e32 v183, v53, v53
	v_fmac_f32_e32 v180, v42, v42
	v_fmac_f32_e32 v181, v46, v46
	v_fmac_f32_e32 v182, v50, v50
	v_fmac_f32_e32 v183, v54, v54
	v_fmac_f32_e32 v180, v43, v43
	v_fmac_f32_e32 v181, v47, v47
	v_fmac_f32_e32 v182, v51, v51
	v_fmac_f32_e32 v183, v55, v55
	v_add_f32_e32 v180, v180, v181
	v_add_f32_e32 v182, v182, v183
	v_add_f32_e32 v180, v180, v182
	s_nop 1
	v_add_f32_dpp v180, v180, v180 quad_perm:[1,0,3,2] row_mask:0xf bank_mask:0xf
	s_nop 1
	v_add_f32_dpp v180, v180, v180 quad_perm:[2,3,0,1] row_mask:0xf bank_mask:0xf
	s_nop 1
	v_add_f32_dpp v180, v180, v180 row_half_mirror row_mask:0xf bank_mask:0xf
	s_nop 1
	v_add_f32_dpp v180, v180, v180 row_mirror row_mask:0xf bank_mask:0xf
	s_nop 1
	v_add_f32_dpp v180, v180, v180 row_bcast:15 row_mask:0xa bank_mask:0xf
	s_nop 1
	v_add_f32_dpp v180, v180, v180 row_bcast:31 row_mask:0xc bank_mask:0xf
	s_nop 0
	v_readlane_b32 s20, v180, 63
	s_nop 1
	v_mov_b32_e32 v185, s20
	v_fma_f32 v185, v185, v2, v4
	v_rsq_f32_e32 v185, v185
	s_nop 0
	v_mul_f32_e32 v40, v40, v185
	v_mul_f32_e32 v41, v41, v185
	v_mul_f32_e32 v42, v42, v185
	v_mul_f32_e32 v43, v43, v185
	v_mul_f32_e32 v44, v44, v185
	v_mul_f32_e32 v45, v45, v185
	v_mul_f32_e32 v46, v46, v185
	v_mul_f32_e32 v47, v47, v185
	v_mul_f32_e32 v48, v48, v185
	v_mul_f32_e32 v49, v49, v185
	v_mul_f32_e32 v50, v50, v185
	v_mul_f32_e32 v51, v51, v185
	v_mul_f32_e32 v52, v52, v185
	v_mul_f32_e32 v53, v53, v185
	v_mul_f32_e32 v54, v54, v185
	v_mul_f32_e32 v55, v55, v185
	s_waitcnt vmcnt(28)
	v_fma_f32 v40, v40, v8, v24
	v_fma_f32 v41, v41, v9, v25
	v_fma_f32 v42, v42, v10, v26
	v_fma_f32 v43, v43, v11, v27
	v_fma_f32 v44, v44, v12, v28
	v_fma_f32 v45, v45, v13, v29
	v_fma_f32 v46, v46, v14, v30
	v_fma_f32 v47, v47, v15, v31
	v_fma_f32 v48, v48, v16, v32
	v_fma_f32 v49, v49, v17, v33
	v_fma_f32 v50, v50, v18, v34
	v_fma_f32 v51, v51, v19, v35
	v_fma_f32 v52, v52, v20, v36
	v_fma_f32 v53, v53, v21, v37
	v_fma_f32 v54, v54, v22, v38
	v_fma_f32 v55, v55, v23, v39
	global_store_dwordx4 v1, v[40:43], s[4:5]
	global_store_dwordx4 v1, v[44:47], s[4:5] offset:1024
	global_store_dwordx4 v1, v[48:51], s[4:5] offset:2048
	global_store_dwordx4 v1, v[52:55], s[4:5] offset:3072
	s_nop 1
	v_add_u32_e32 v170, 0x3000000, v1
	global_load_dwordx4 v[40:43], v170, s[4:5]
	global_load_dwordx4 v[44:47], v170, s[4:5] offset:1024
	global_load_dwordx4 v[48:51], v170, s[4:5] offset:2048
	global_load_dwordx4 v[52:55], v170, s[4:5] offset:3072
	s_waitcnt vmcnt(32)
	v_add_f32_e32 v180, v56, v57
	v_add_f32_e32 v181, v60, v61
	v_add_f32_e32 v182, v64, v65
	v_add_f32_e32 v183, v68, v69
	v_add_f32_e32 v180, v180, v58
	v_add_f32_e32 v181, v181, v62
	v_add_f32_e32 v182, v182, v66
	v_add_f32_e32 v183, v183, v70
	v_add_f32_e32 v180, v180, v59
	v_add_f32_e32 v181, v181, v63
	v_add_f32_e32 v182, v182, v67
	v_add_f32_e32 v183, v183, v71
	v_add_f32_e32 v180, v180, v181
	v_add_f32_e32 v182, v182, v183
	v_add_f32_e32 v180, v180, v182
	s_nop 1
	v_add_f32_dpp v180, v180, v180 quad_perm:[1,0,3,2] row_mask:0xf bank_mask:0xf
	s_nop 1
	v_add_f32_dpp v180, v180, v180 quad_perm:[2,3,0,1] row_mask:0xf bank_mask:0xf
	s_nop 1
	v_add_f32_dpp v180, v180, v180 row_half_mirror row_mask:0xf bank_mask:0xf
	s_nop 1
	v_add_f32_dpp v180, v180, v180 row_mirror row_mask:0xf bank_mask:0xf
	s_nop 1
	v_add_f32_dpp v180, v180, v180 row_bcast:15 row_mask:0xa bank_mask:0xf
	s_nop 1
	v_add_f32_dpp v180, v180, v180 row_bcast:31 row_mask:0xc bank_mask:0xf
	s_nop 0
	v_readlane_b32 s20, v180, 63
	s_nop 1
	v_mul_f32_e32 v184, s20, v2
	v_sub_f32_e32 v56, v56, v184
	v_sub_f32_e32 v57, v57, v184
	v_sub_f32_e32 v58, v58, v184
	v_sub_f32_e32 v59, v59, v184
	v_sub_f32_e32 v60, v60, v184
	v_sub_f32_e32 v61, v61, v184
	v_sub_f32_e32 v62, v62, v184
	v_sub_f32_e32 v63, v63, v184
	v_sub_f32_e32 v64, v64, v184
	v_sub_f32_e32 v65, v65, v184
	v_sub_f32_e32 v66, v66, v184
	v_sub_f32_e32 v67, v67, v184
	v_sub_f32_e32 v68, v68, v184
	v_sub_f32_e32 v69, v69, v184
	v_sub_f32_e32 v70, v70, v184
	v_sub_f32_e32 v71, v71, v184
	v_mul_f32_e32 v180, v56, v56
	v_mul_f32_e32 v181, v60, v60
	v_mul_f32_e32 v182, v64, v64
	v_mul_f32_e32 v183, v68, v68
	v_fmac_f32_e32 v180, v57, v57
	v_fmac_f32_e32 v181, v61, v61
	v_fmac_f32_e32 v182, v65, v65
	v_fmac_f32_e32 v183, v69, v69
	v_fmac_f32_e32 v180, v58, v58
	v_fmac_f32_e32 v181, v62, v62
	v_fmac_f32_e32 v182, v66, v66
	v_fmac_f32_e32 v183, v70, v70
	v_fmac_f32_e32 v180, v59, v59
	v_fmac_f32_e32 v181, v63, v63
	v_fmac_f32_e32 v182, v67, v67
	v_fmac_f32_e32 v183, v71, v71
	v_add_f32_e32 v180, v180, v181
	v_add_f32_e32 v182, v182, v183
	v_add_f32_e32 v180, v180, v182
	s_nop 1
	v_add_f32_dpp v180, v180, v180 quad_perm:[1,0,3,2] row_mask:0xf bank_mask:0xf
	s_nop 1
	v_add_f32_dpp v180, v180, v180 quad_perm:[2,3,0,1] row_mask:0xf bank_mask:0xf
	s_nop 1
	v_add_f32_dpp v180, v180, v180 row_half_mirror row_mask:0xf bank_mask:0xf
	s_nop 1
	v_add_f32_dpp v180, v180, v180 row_mirror row_mask:0xf bank_mask:0xf
	s_nop 1
	v_add_f32_dpp v180, v180, v180 row_bcast:15 row_mask:0xa bank_mask:0xf
	s_nop 1
	v_add_f32_dpp v180, v180, v180 row_bcast:31 row_mask:0xc bank_mask:0xf
	s_nop 0
	v_readlane_b32 s20, v180, 63
	s_nop 1
	v_mov_b32_e32 v185, s20
	v_fma_f32 v185, v185, v2, v4
	v_rsq_f32_e32 v185, v185
	s_nop 0
	v_mul_f32_e32 v56, v56, v185
	v_mul_f32_e32 v57, v57, v185
	v_mul_f32_e32 v58, v58, v185
	v_mul_f32_e32 v59, v59, v185
	v_mul_f32_e32 v60, v60, v185
	v_mul_f32_e32 v61, v61, v185
	v_mul_f32_e32 v62, v62, v185
	v_mul_f32_e32 v63, v63, v185
	v_mul_f32_e32 v64, v64, v185
	v_mul_f32_e32 v65, v65, v185
	v_mul_f32_e32 v66, v66, v185
	v_mul_f32_e32 v67, v67, v185
	v_mul_f32_e32 v68, v68, v185
	v_mul_f32_e32 v69, v69, v185
	v_mul_f32_e32 v70, v70, v185
	v_mul_f32_e32 v71, v71, v185
	v_fma_f32 v56, v56, v8, v24
	v_fma_f32 v57, v57, v9, v25
	v_fma_f32 v58, v58, v10, v26
	v_fma_f32 v59, v59, v11, v27
	v_fma_f32 v60, v60, v12, v28
	v_fma_f32 v61, v61, v13, v29
	v_fma_f32 v62, v62, v14, v30
	v_fma_f32 v63, v63, v15, v31
	v_fma_f32 v64, v64, v16, v32
	v_fma_f32 v65, v65, v17, v33
	v_fma_f32 v66, v66, v18, v34
	v_fma_f32 v67, v67, v19, v35
	v_fma_f32 v68, v68, v20, v36
	v_fma_f32 v69, v69, v21, v37
	v_fma_f32 v70, v70, v22, v38
	v_fma_f32 v71, v71, v23, v39
	v_add_u32_e32 v171, 0x600000, v1
	global_store_dwordx4 v171, v[56:59], s[4:5]
	global_store_dwordx4 v171, v[60:63], s[4:5] offset:1024
	global_store_dwordx4 v171, v[64:67], s[4:5] offset:2048
	global_store_dwordx4 v171, v[68:71], s[4:5] offset:3072
	s_nop 1
	v_add_u32_e32 v170, 0x3600000, v1
	global_load_dwordx4 v[56:59], v170, s[4:5]
	global_load_dwordx4 v[60:63], v170, s[4:5] offset:1024
	global_load_dwordx4 v[64:67], v170, s[4:5] offset:2048
	global_load_dwordx4 v[68:71], v170, s[4:5] offset:3072
	s_waitcnt vmcnt(36)
	v_add_f32_e32 v180, v72, v73
	v_add_f32_e32 v181, v76, v77
	v_add_f32_e32 v182, v80, v81
	v_add_f32_e32 v183, v84, v85
	v_add_f32_e32 v180, v180, v74
	v_add_f32_e32 v181, v181, v78
	v_add_f32_e32 v182, v182, v82
	v_add_f32_e32 v183, v183, v86
	v_add_f32_e32 v180, v180, v75
	v_add_f32_e32 v181, v181, v79
	v_add_f32_e32 v182, v182, v83
	v_add_f32_e32 v183, v183, v87
	v_add_f32_e32 v180, v180, v181
	v_add_f32_e32 v182, v182, v183
	v_add_f32_e32 v180, v180, v182
	s_nop 1
	v_add_f32_dpp v180, v180, v180 quad_perm:[1,0,3,2] row_mask:0xf bank_mask:0xf
	s_nop 1
	v_add_f32_dpp v180, v180, v180 quad_perm:[2,3,0,1] row_mask:0xf bank_mask:0xf
	s_nop 1
	v_add_f32_dpp v180, v180, v180 row_half_mirror row_mask:0xf bank_mask:0xf
	s_nop 1
	v_add_f32_dpp v180, v180, v180 row_mirror row_mask:0xf bank_mask:0xf
	s_nop 1
	v_add_f32_dpp v180, v180, v180 row_bcast:15 row_mask:0xa bank_mask:0xf
	s_nop 1
	v_add_f32_dpp v180, v180, v180 row_bcast:31 row_mask:0xc bank_mask:0xf
	s_nop 0
	v_readlane_b32 s20, v180, 63
	s_nop 1
	v_mul_f32_e32 v184, s20, v2
	v_sub_f32_e32 v72, v72, v184
	v_sub_f32_e32 v73, v73, v184
	v_sub_f32_e32 v74, v74, v184
	v_sub_f32_e32 v75, v75, v184
	v_sub_f32_e32 v76, v76, v184
	v_sub_f32_e32 v77, v77, v184
	v_sub_f32_e32 v78, v78, v184
	v_sub_f32_e32 v79, v79, v184
	v_sub_f32_e32 v80, v80, v184
	v_sub_f32_e32 v81, v81, v184
	v_sub_f32_e32 v82, v82, v184
	v_sub_f32_e32 v83, v83, v184
	v_sub_f32_e32 v84, v84, v184
	v_sub_f32_e32 v85, v85, v184
	v_sub_f32_e32 v86, v86, v184
	v_sub_f32_e32 v87, v87, v184
	v_mul_f32_e32 v180, v72, v72
	v_mul_f32_e32 v181, v76, v76
	v_mul_f32_e32 v182, v80, v80
	v_mul_f32_e32 v183, v84, v84
	v_fmac_f32_e32 v180, v73, v73
	v_fmac_f32_e32 v181, v77, v77
	v_fmac_f32_e32 v182, v81, v81
	v_fmac_f32_e32 v183, v85, v85
	v_fmac_f32_e32 v180, v74, v74
	v_fmac_f32_e32 v181, v78, v78
	v_fmac_f32_e32 v182, v82, v82
	v_fmac_f32_e32 v183, v86, v86
	v_fmac_f32_e32 v180, v75, v75
	v_fmac_f32_e32 v181, v79, v79
	v_fmac_f32_e32 v182, v83, v83
	v_fmac_f32_e32 v183, v87, v87
	v_add_f32_e32 v180, v180, v181
	v_add_f32_e32 v182, v182, v183
	v_add_f32_e32 v180, v180, v182
	s_nop 1
	v_add_f32_dpp v180, v180, v180 quad_perm:[1,0,3,2] row_mask:0xf bank_mask:0xf
	s_nop 1
	v_add_f32_dpp v180, v180, v180 quad_perm:[2,3,0,1] row_mask:0xf bank_mask:0xf
	s_nop 1
	v_add_f32_dpp v180, v180, v180 row_half_mirror row_mask:0xf bank_mask:0xf
	s_nop 1
	v_add_f32_dpp v180, v180, v180 row_mirror row_mask:0xf bank_mask:0xf
	s_nop 1
	v_add_f32_dpp v180, v180, v180 row_bcast:15 row_mask:0xa bank_mask:0xf
	s_nop 1
	v_add_f32_dpp v180, v180, v180 row_bcast:31 row_mask:0xc bank_mask:0xf
	s_nop 0
	v_readlane_b32 s20, v180, 63
	s_nop 1
	v_mov_b32_e32 v185, s20
	v_fma_f32 v185, v185, v2, v4
	v_rsq_f32_e32 v185, v185
	s_nop 0
	v_mul_f32_e32 v72, v72, v185
	v_mul_f32_e32 v73, v73, v185
	v_mul_f32_e32 v74, v74, v185
	v_mul_f32_e32 v75, v75, v185
	v_mul_f32_e32 v76, v76, v185
	v_mul_f32_e32 v77, v77, v185
	v_mul_f32_e32 v78, v78, v185
	v_mul_f32_e32 v79, v79, v185
	v_mul_f32_e32 v80, v80, v185
	v_mul_f32_e32 v81, v81, v185
	v_mul_f32_e32 v82, v82, v185
	v_mul_f32_e32 v83, v83, v185
	v_mul_f32_e32 v84, v84, v185
	v_mul_f32_e32 v85, v85, v185
	v_mul_f32_e32 v86, v86, v185
	v_mul_f32_e32 v87, v87, v185
	v_fma_f32 v72, v72, v8, v24
	v_fma_f32 v73, v73, v9, v25
	v_fma_f32 v74, v74, v10, v26
	v_fma_f32 v75, v75, v11, v27
	v_fma_f32 v76, v76, v12, v28
	v_fma_f32 v77, v77, v13, v29
	v_fma_f32 v78, v78, v14, v30
	v_fma_f32 v79, v79, v15, v31
	v_fma_f32 v80, v80, v16, v32
	v_fma_f32 v81, v81, v17, v33
	v_fma_f32 v82, v82, v18, v34
	v_fma_f32 v83, v83, v19, v35
	v_fma_f32 v84, v84, v20, v36
	v_fma_f32 v85, v85, v21, v37
	v_fma_f32 v86, v86, v22, v38
	v_fma_f32 v87, v87, v23, v39
	v_add_u32_e32 v171, 0xc00000, v1
	global_store_dwordx4 v171, v[72:75], s[4:5]
	global_store_dwordx4 v171, v[76:79], s[4:5] offset:1024
	global_store_dwordx4 v171, v[80:83], s[4:5] offset:2048
	global_store_dwordx4 v171, v[84:87], s[4:5] offset:3072
	s_waitcnt vmcnt(36)
	v_add_f32_e32 v180, v88, v89
	v_add_f32_e32 v181, v92, v93
	v_add_f32_e32 v182, v96, v97
	v_add_f32_e32 v183, v100, v101
	v_add_f32_e32 v180, v180, v90
	v_add_f32_e32 v181, v181, v94
	v_add_f32_e32 v182, v182, v98
	v_add_f32_e32 v183, v183, v102
	v_add_f32_e32 v180, v180, v91
	v_add_f32_e32 v181, v181, v95
	v_add_f32_e32 v182, v182, v99
	v_add_f32_e32 v183, v183, v103
	v_add_f32_e32 v180, v180, v181
	v_add_f32_e32 v182, v182, v183
	v_add_f32_e32 v180, v180, v182
	s_nop 1
	v_add_f32_dpp v180, v180, v180 quad_perm:[1,0,3,2] row_mask:0xf bank_mask:0xf
	s_nop 1
	v_add_f32_dpp v180, v180, v180 quad_perm:[2,3,0,1] row_mask:0xf bank_mask:0xf
	s_nop 1
	v_add_f32_dpp v180, v180, v180 row_half_mirror row_mask:0xf bank_mask:0xf
	s_nop 1
	v_add_f32_dpp v180, v180, v180 row_mirror row_mask:0xf bank_mask:0xf
	s_nop 1
	v_add_f32_dpp v180, v180, v180 row_bcast:15 row_mask:0xa bank_mask:0xf
	s_nop 1
	v_add_f32_dpp v180, v180, v180 row_bcast:31 row_mask:0xc bank_mask:0xf
	s_nop 0
	v_readlane_b32 s20, v180, 63
	s_nop 1
	v_mul_f32_e32 v184, s20, v2
	v_sub_f32_e32 v88, v88, v184
	v_sub_f32_e32 v89, v89, v184
	v_sub_f32_e32 v90, v90, v184
	v_sub_f32_e32 v91, v91, v184
	v_sub_f32_e32 v92, v92, v184
	v_sub_f32_e32 v93, v93, v184
	v_sub_f32_e32 v94, v94, v184
	v_sub_f32_e32 v95, v95, v184
	v_sub_f32_e32 v96, v96, v184
	v_sub_f32_e32 v97, v97, v184
	v_sub_f32_e32 v98, v98, v184
	v_sub_f32_e32 v99, v99, v184
	v_sub_f32_e32 v100, v100, v184
	v_sub_f32_e32 v101, v101, v184
	v_sub_f32_e32 v102, v102, v184
	v_sub_f32_e32 v103, v103, v184
	v_mul_f32_e32 v180, v88, v88
	v_mul_f32_e32 v181, v92, v92
	v_mul_f32_e32 v182, v96, v96
	v_mul_f32_e32 v183, v100, v100
	v_fmac_f32_e32 v180, v89, v89
	v_fmac_f32_e32 v181, v93, v93
	v_fmac_f32_e32 v182, v97, v97
	v_fmac_f32_e32 v183, v101, v101
	v_fmac_f32_e32 v180, v90, v90
	v_fmac_f32_e32 v181, v94, v94
	v_fmac_f32_e32 v182, v98, v98
	v_fmac_f32_e32 v183, v102, v102
	v_fmac_f32_e32 v180, v91, v91
	v_fmac_f32_e32 v181, v95, v95
	v_fmac_f32_e32 v182, v99, v99
	v_fmac_f32_e32 v183, v103, v103
	v_add_f32_e32 v180, v180, v181
	v_add_f32_e32 v182, v182, v183
	v_add_f32_e32 v180, v180, v182
	s_nop 1
	v_add_f32_dpp v180, v180, v180 quad_perm:[1,0,3,2] row_mask:0xf bank_mask:0xf
	s_nop 1
	v_add_f32_dpp v180, v180, v180 quad_perm:[2,3,0,1] row_mask:0xf bank_mask:0xf
	s_nop 1
	v_add_f32_dpp v180, v180, v180 row_half_mirror row_mask:0xf bank_mask:0xf
	s_nop 1
	v_add_f32_dpp v180, v180, v180 row_mirror row_mask:0xf bank_mask:0xf
	s_nop 1
	v_add_f32_dpp v180, v180, v180 row_bcast:15 row_mask:0xa bank_mask:0xf
	s_nop 1
	v_add_f32_dpp v180, v180, v180 row_bcast:31 row_mask:0xc bank_mask:0xf
	s_nop 0
	v_readlane_b32 s20, v180, 63
	s_nop 1
	v_mov_b32_e32 v185, s20
	v_fma_f32 v185, v185, v2, v4
	v_rsq_f32_e32 v185, v185
	s_nop 0
	v_mul_f32_e32 v88, v88, v185
	v_mul_f32_e32 v89, v89, v185
	v_mul_f32_e32 v90, v90, v185
	v_mul_f32_e32 v91, v91, v185
	v_mul_f32_e32 v92, v92, v185
	v_mul_f32_e32 v93, v93, v185
	v_mul_f32_e32 v94, v94, v185
	v_mul_f32_e32 v95, v95, v185
	v_mul_f32_e32 v96, v96, v185
	v_mul_f32_e32 v97, v97, v185
	v_mul_f32_e32 v98, v98, v185
	v_mul_f32_e32 v99, v99, v185
	v_mul_f32_e32 v100, v100, v185
	v_mul_f32_e32 v101, v101, v185
	v_mul_f32_e32 v102, v102, v185
	v_mul_f32_e32 v103, v103, v185
	v_fma_f32 v88, v88, v8, v24
	v_fma_f32 v89, v89, v9, v25
	v_fma_f32 v90, v90, v10, v26
	v_fma_f32 v91, v91, v11, v27
	v_fma_f32 v92, v92, v12, v28
	v_fma_f32 v93, v93, v13, v29
	v_fma_f32 v94, v94, v14, v30
	v_fma_f32 v95, v95, v15, v31
	v_fma_f32 v96, v96, v16, v32
	v_fma_f32 v97, v97, v17, v33
	v_fma_f32 v98, v98, v18, v34
	v_fma_f32 v99, v99, v19, v35
	v_fma_f32 v100, v100, v20, v36
	v_fma_f32 v101, v101, v21, v37
	v_fma_f32 v102, v102, v22, v38
	v_fma_f32 v103, v103, v23, v39
	v_add_u32_e32 v171, 0x1200000, v1
	global_store_dwordx4 v171, v[88:91], s[4:5]
	global_store_dwordx4 v171, v[92:95], s[4:5] offset:1024
	global_store_dwordx4 v171, v[96:99], s[4:5] offset:2048
	global_store_dwordx4 v171, v[100:103], s[4:5] offset:3072
	s_waitcnt vmcnt(36)
	v_add_f32_e32 v180, v104, v105
	v_add_f32_e32 v181, v108, v109
	v_add_f32_e32 v182, v112, v113
	v_add_f32_e32 v183, v116, v117
	v_add_f32_e32 v180, v180, v106
	v_add_f32_e32 v181, v181, v110
	v_add_f32_e32 v182, v182, v114
	v_add_f32_e32 v183, v183, v118
	v_add_f32_e32 v180, v180, v107
	v_add_f32_e32 v181, v181, v111
	v_add_f32_e32 v182, v182, v115
	v_add_f32_e32 v183, v183, v119
	v_add_f32_e32 v180, v180, v181
	v_add_f32_e32 v182, v182, v183
	v_add_f32_e32 v180, v180, v182
	s_nop 1
	v_add_f32_dpp v180, v180, v180 quad_perm:[1,0,3,2] row_mask:0xf bank_mask:0xf
	s_nop 1
	v_add_f32_dpp v180, v180, v180 quad_perm:[2,3,0,1] row_mask:0xf bank_mask:0xf
	s_nop 1
	v_add_f32_dpp v180, v180, v180 row_half_mirror row_mask:0xf bank_mask:0xf
	s_nop 1
	v_add_f32_dpp v180, v180, v180 row_mirror row_mask:0xf bank_mask:0xf
	s_nop 1
	v_add_f32_dpp v180, v180, v180 row_bcast:15 row_mask:0xa bank_mask:0xf
	s_nop 1
	v_add_f32_dpp v180, v180, v180 row_bcast:31 row_mask:0xc bank_mask:0xf
	s_nop 0
	v_readlane_b32 s20, v180, 63
	s_nop 1
	v_mul_f32_e32 v184, s20, v2
	v_sub_f32_e32 v104, v104, v184
	v_sub_f32_e32 v105, v105, v184
	v_sub_f32_e32 v106, v106, v184
	v_sub_f32_e32 v107, v107, v184
	v_sub_f32_e32 v108, v108, v184
	v_sub_f32_e32 v109, v109, v184
	v_sub_f32_e32 v110, v110, v184
	v_sub_f32_e32 v111, v111, v184
	v_sub_f32_e32 v112, v112, v184
	v_sub_f32_e32 v113, v113, v184
	v_sub_f32_e32 v114, v114, v184
	v_sub_f32_e32 v115, v115, v184
	v_sub_f32_e32 v116, v116, v184
	v_sub_f32_e32 v117, v117, v184
	v_sub_f32_e32 v118, v118, v184
	v_sub_f32_e32 v119, v119, v184
	v_mul_f32_e32 v180, v104, v104
	v_mul_f32_e32 v181, v108, v108
	v_mul_f32_e32 v182, v112, v112
	v_mul_f32_e32 v183, v116, v116
	v_fmac_f32_e32 v180, v105, v105
	v_fmac_f32_e32 v181, v109, v109
	v_fmac_f32_e32 v182, v113, v113
	v_fmac_f32_e32 v183, v117, v117
	v_fmac_f32_e32 v180, v106, v106
	v_fmac_f32_e32 v181, v110, v110
	v_fmac_f32_e32 v182, v114, v114
	v_fmac_f32_e32 v183, v118, v118
	v_fmac_f32_e32 v180, v107, v107
	v_fmac_f32_e32 v181, v111, v111
	v_fmac_f32_e32 v182, v115, v115
	v_fmac_f32_e32 v183, v119, v119
	v_add_f32_e32 v180, v180, v181
	v_add_f32_e32 v182, v182, v183
	v_add_f32_e32 v180, v180, v182
	s_nop 1
	v_add_f32_dpp v180, v180, v180 quad_perm:[1,0,3,2] row_mask:0xf bank_mask:0xf
	s_nop 1
	v_add_f32_dpp v180, v180, v180 quad_perm:[2,3,0,1] row_mask:0xf bank_mask:0xf
	s_nop 1
	v_add_f32_dpp v180, v180, v180 row_half_mirror row_mask:0xf bank_mask:0xf
	s_nop 1
	v_add_f32_dpp v180, v180, v180 row_mirror row_mask:0xf bank_mask:0xf
	s_nop 1
	v_add_f32_dpp v180, v180, v180 row_bcast:15 row_mask:0xa bank_mask:0xf
	s_nop 1
	v_add_f32_dpp v180, v180, v180 row_bcast:31 row_mask:0xc bank_mask:0xf
	s_nop 0
	v_readlane_b32 s20, v180, 63
	s_nop 1
	v_mov_b32_e32 v185, s20
	v_fma_f32 v185, v185, v2, v4
	v_rsq_f32_e32 v185, v185
	s_nop 0
	v_mul_f32_e32 v104, v104, v185
	v_mul_f32_e32 v105, v105, v185
	v_mul_f32_e32 v106, v106, v185
	v_mul_f32_e32 v107, v107, v185
	v_mul_f32_e32 v108, v108, v185
	v_mul_f32_e32 v109, v109, v185
	v_mul_f32_e32 v110, v110, v185
	v_mul_f32_e32 v111, v111, v185
	v_mul_f32_e32 v112, v112, v185
	v_mul_f32_e32 v113, v113, v185
	v_mul_f32_e32 v114, v114, v185
	v_mul_f32_e32 v115, v115, v185
	v_mul_f32_e32 v116, v116, v185
	v_mul_f32_e32 v117, v117, v185
	v_mul_f32_e32 v118, v118, v185
	v_mul_f32_e32 v119, v119, v185
	v_fma_f32 v104, v104, v8, v24
	v_fma_f32 v105, v105, v9, v25
	v_fma_f32 v106, v106, v10, v26
	v_fma_f32 v107, v107, v11, v27
	v_fma_f32 v108, v108, v12, v28
	v_fma_f32 v109, v109, v13, v29
	v_fma_f32 v110, v110, v14, v30
	v_fma_f32 v111, v111, v15, v31
	v_fma_f32 v112, v112, v16, v32
	v_fma_f32 v113, v113, v17, v33
	v_fma_f32 v114, v114, v18, v34
	v_fma_f32 v115, v115, v19, v35
	v_fma_f32 v116, v116, v20, v36
	v_fma_f32 v117, v117, v21, v37
	v_fma_f32 v118, v118, v22, v38
	v_fma_f32 v119, v119, v23, v39
	v_add_u32_e32 v171, 0x1800000, v1
	global_store_dwordx4 v171, v[104:107], s[4:5]
	global_store_dwordx4 v171, v[108:111], s[4:5] offset:1024
	global_store_dwordx4 v171, v[112:115], s[4:5] offset:2048
	global_store_dwordx4 v171, v[116:119], s[4:5] offset:3072
	s_waitcnt vmcnt(36)
	v_add_f32_e32 v180, v120, v121
	v_add_f32_e32 v181, v124, v125
	v_add_f32_e32 v182, v128, v129
	v_add_f32_e32 v183, v132, v133
	v_add_f32_e32 v180, v180, v122
	v_add_f32_e32 v181, v181, v126
	v_add_f32_e32 v182, v182, v130
	v_add_f32_e32 v183, v183, v134
	v_add_f32_e32 v180, v180, v123
	v_add_f32_e32 v181, v181, v127
	v_add_f32_e32 v182, v182, v131
	v_add_f32_e32 v183, v183, v135
	v_add_f32_e32 v180, v180, v181
	v_add_f32_e32 v182, v182, v183
	v_add_f32_e32 v180, v180, v182
	s_nop 1
	v_add_f32_dpp v180, v180, v180 quad_perm:[1,0,3,2] row_mask:0xf bank_mask:0xf
	s_nop 1
	v_add_f32_dpp v180, v180, v180 quad_perm:[2,3,0,1] row_mask:0xf bank_mask:0xf
	s_nop 1
	v_add_f32_dpp v180, v180, v180 row_half_mirror row_mask:0xf bank_mask:0xf
	s_nop 1
	v_add_f32_dpp v180, v180, v180 row_mirror row_mask:0xf bank_mask:0xf
	s_nop 1
	v_add_f32_dpp v180, v180, v180 row_bcast:15 row_mask:0xa bank_mask:0xf
	s_nop 1
	v_add_f32_dpp v180, v180, v180 row_bcast:31 row_mask:0xc bank_mask:0xf
	s_nop 0
	v_readlane_b32 s20, v180, 63
	s_nop 1
	v_mul_f32_e32 v184, s20, v2
	v_sub_f32_e32 v120, v120, v184
	v_sub_f32_e32 v121, v121, v184
	v_sub_f32_e32 v122, v122, v184
	v_sub_f32_e32 v123, v123, v184
	v_sub_f32_e32 v124, v124, v184
	v_sub_f32_e32 v125, v125, v184
	v_sub_f32_e32 v126, v126, v184
	v_sub_f32_e32 v127, v127, v184
	v_sub_f32_e32 v128, v128, v184
	v_sub_f32_e32 v129, v129, v184
	v_sub_f32_e32 v130, v130, v184
	v_sub_f32_e32 v131, v131, v184
	v_sub_f32_e32 v132, v132, v184
	v_sub_f32_e32 v133, v133, v184
	v_sub_f32_e32 v134, v134, v184
	v_sub_f32_e32 v135, v135, v184
	v_mul_f32_e32 v180, v120, v120
	v_mul_f32_e32 v181, v124, v124
	v_mul_f32_e32 v182, v128, v128
	v_mul_f32_e32 v183, v132, v132
	v_fmac_f32_e32 v180, v121, v121
	v_fmac_f32_e32 v181, v125, v125
	v_fmac_f32_e32 v182, v129, v129
	v_fmac_f32_e32 v183, v133, v133
	v_fmac_f32_e32 v180, v122, v122
	v_fmac_f32_e32 v181, v126, v126
	v_fmac_f32_e32 v182, v130, v130
	v_fmac_f32_e32 v183, v134, v134
	v_fmac_f32_e32 v180, v123, v123
	v_fmac_f32_e32 v181, v127, v127
	v_fmac_f32_e32 v182, v131, v131
	v_fmac_f32_e32 v183, v135, v135
	v_add_f32_e32 v180, v180, v181
	v_add_f32_e32 v182, v182, v183
	v_add_f32_e32 v180, v180, v182
	s_nop 1
	v_add_f32_dpp v180, v180, v180 quad_perm:[1,0,3,2] row_mask:0xf bank_mask:0xf
	s_nop 1
	v_add_f32_dpp v180, v180, v180 quad_perm:[2,3,0,1] row_mask:0xf bank_mask:0xf
	s_nop 1
	v_add_f32_dpp v180, v180, v180 row_half_mirror row_mask:0xf bank_mask:0xf
	s_nop 1
	v_add_f32_dpp v180, v180, v180 row_mirror row_mask:0xf bank_mask:0xf
	s_nop 1
	v_add_f32_dpp v180, v180, v180 row_bcast:15 row_mask:0xa bank_mask:0xf
	s_nop 1
	v_add_f32_dpp v180, v180, v180 row_bcast:31 row_mask:0xc bank_mask:0xf
	s_nop 0
	v_readlane_b32 s20, v180, 63
	s_nop 1
	v_mov_b32_e32 v185, s20
	v_fma_f32 v185, v185, v2, v4
	v_rsq_f32_e32 v185, v185
	s_nop 0
	v_mul_f32_e32 v120, v120, v185
	v_mul_f32_e32 v121, v121, v185
	v_mul_f32_e32 v122, v122, v185
	v_mul_f32_e32 v123, v123, v185
	v_mul_f32_e32 v124, v124, v185
	v_mul_f32_e32 v125, v125, v185
	v_mul_f32_e32 v126, v126, v185
	v_mul_f32_e32 v127, v127, v185
	v_mul_f32_e32 v128, v128, v185
	v_mul_f32_e32 v129, v129, v185
	v_mul_f32_e32 v130, v130, v185
	v_mul_f32_e32 v131, v131, v185
	v_mul_f32_e32 v132, v132, v185
	v_mul_f32_e32 v133, v133, v185
	v_mul_f32_e32 v134, v134, v185
	v_mul_f32_e32 v135, v135, v185
	v_fma_f32 v120, v120, v8, v24
	v_fma_f32 v121, v121, v9, v25
	v_fma_f32 v122, v122, v10, v26
	v_fma_f32 v123, v123, v11, v27
	v_fma_f32 v124, v124, v12, v28
	v_fma_f32 v125, v125, v13, v29
	v_fma_f32 v126, v126, v14, v30
	v_fma_f32 v127, v127, v15, v31
	v_fma_f32 v128, v128, v16, v32
	v_fma_f32 v129, v129, v17, v33
	v_fma_f32 v130, v130, v18, v34
	v_fma_f32 v131, v131, v19, v35
	v_fma_f32 v132, v132, v20, v36
	v_fma_f32 v133, v133, v21, v37
	v_fma_f32 v134, v134, v22, v38
	v_fma_f32 v135, v135, v23, v39
	v_add_u32_e32 v171, 0x1e00000, v1
	global_store_dwordx4 v171, v[120:123], s[4:5]
	global_store_dwordx4 v171, v[124:127], s[4:5] offset:1024
	global_store_dwordx4 v171, v[128:131], s[4:5] offset:2048
	global_store_dwordx4 v171, v[132:135], s[4:5] offset:3072
	s_waitcnt vmcnt(36)
	v_add_f32_e32 v180, v136, v137
	v_add_f32_e32 v181, v140, v141
	v_add_f32_e32 v182, v144, v145
	v_add_f32_e32 v183, v148, v149
	v_add_f32_e32 v180, v180, v138
	v_add_f32_e32 v181, v181, v142
	v_add_f32_e32 v182, v182, v146
	v_add_f32_e32 v183, v183, v150
	v_add_f32_e32 v180, v180, v139
	v_add_f32_e32 v181, v181, v143
	v_add_f32_e32 v182, v182, v147
	v_add_f32_e32 v183, v183, v151
	v_add_f32_e32 v180, v180, v181
	v_add_f32_e32 v182, v182, v183
	v_add_f32_e32 v180, v180, v182
	s_nop 1
	v_add_f32_dpp v180, v180, v180 quad_perm:[1,0,3,2] row_mask:0xf bank_mask:0xf
	s_nop 1
	v_add_f32_dpp v180, v180, v180 quad_perm:[2,3,0,1] row_mask:0xf bank_mask:0xf
	s_nop 1
	v_add_f32_dpp v180, v180, v180 row_half_mirror row_mask:0xf bank_mask:0xf
	s_nop 1
	v_add_f32_dpp v180, v180, v180 row_mirror row_mask:0xf bank_mask:0xf
	s_nop 1
	v_add_f32_dpp v180, v180, v180 row_bcast:15 row_mask:0xa bank_mask:0xf
	s_nop 1
	v_add_f32_dpp v180, v180, v180 row_bcast:31 row_mask:0xc bank_mask:0xf
	s_nop 0
	v_readlane_b32 s20, v180, 63
	s_nop 1
	v_mul_f32_e32 v184, s20, v2
	v_sub_f32_e32 v136, v136, v184
	v_sub_f32_e32 v137, v137, v184
	v_sub_f32_e32 v138, v138, v184
	v_sub_f32_e32 v139, v139, v184
	v_sub_f32_e32 v140, v140, v184
	v_sub_f32_e32 v141, v141, v184
	v_sub_f32_e32 v142, v142, v184
	v_sub_f32_e32 v143, v143, v184
	v_sub_f32_e32 v144, v144, v184
	v_sub_f32_e32 v145, v145, v184
	v_sub_f32_e32 v146, v146, v184
	v_sub_f32_e32 v147, v147, v184
	v_sub_f32_e32 v148, v148, v184
	v_sub_f32_e32 v149, v149, v184
	v_sub_f32_e32 v150, v150, v184
	v_sub_f32_e32 v151, v151, v184
	v_mul_f32_e32 v180, v136, v136
	v_mul_f32_e32 v181, v140, v140
	v_mul_f32_e32 v182, v144, v144
	v_mul_f32_e32 v183, v148, v148
	v_fmac_f32_e32 v180, v137, v137
	v_fmac_f32_e32 v181, v141, v141
	v_fmac_f32_e32 v182, v145, v145
	v_fmac_f32_e32 v183, v149, v149
	v_fmac_f32_e32 v180, v138, v138
	v_fmac_f32_e32 v181, v142, v142
	v_fmac_f32_e32 v182, v146, v146
	v_fmac_f32_e32 v183, v150, v150
	v_fmac_f32_e32 v180, v139, v139
	v_fmac_f32_e32 v181, v143, v143
	v_fmac_f32_e32 v182, v147, v147
	v_fmac_f32_e32 v183, v151, v151
	v_add_f32_e32 v180, v180, v181
	v_add_f32_e32 v182, v182, v183
	v_add_f32_e32 v180, v180, v182
	s_nop 1
	v_add_f32_dpp v180, v180, v180 quad_perm:[1,0,3,2] row_mask:0xf bank_mask:0xf
	s_nop 1
	v_add_f32_dpp v180, v180, v180 quad_perm:[2,3,0,1] row_mask:0xf bank_mask:0xf
	s_nop 1
	v_add_f32_dpp v180, v180, v180 row_half_mirror row_mask:0xf bank_mask:0xf
	s_nop 1
	v_add_f32_dpp v180, v180, v180 row_mirror row_mask:0xf bank_mask:0xf
	s_nop 1
	v_add_f32_dpp v180, v180, v180 row_bcast:15 row_mask:0xa bank_mask:0xf
	s_nop 1
	v_add_f32_dpp v180, v180, v180 row_bcast:31 row_mask:0xc bank_mask:0xf
	s_nop 0
	v_readlane_b32 s20, v180, 63
	s_nop 1
	v_mov_b32_e32 v185, s20
	v_fma_f32 v185, v185, v2, v4
	v_rsq_f32_e32 v185, v185
	s_nop 0
	v_mul_f32_e32 v136, v136, v185
	v_mul_f32_e32 v137, v137, v185
	v_mul_f32_e32 v138, v138, v185
	v_mul_f32_e32 v139, v139, v185
	v_mul_f32_e32 v140, v140, v185
	v_mul_f32_e32 v141, v141, v185
	v_mul_f32_e32 v142, v142, v185
	v_mul_f32_e32 v143, v143, v185
	v_mul_f32_e32 v144, v144, v185
	v_mul_f32_e32 v145, v145, v185
	v_mul_f32_e32 v146, v146, v185
	v_mul_f32_e32 v147, v147, v185
	v_mul_f32_e32 v148, v148, v185
	v_mul_f32_e32 v149, v149, v185
	v_mul_f32_e32 v150, v150, v185
	v_mul_f32_e32 v151, v151, v185
	v_fma_f32 v136, v136, v8, v24
	v_fma_f32 v137, v137, v9, v25
	v_fma_f32 v138, v138, v10, v26
	v_fma_f32 v139, v139, v11, v27
	v_fma_f32 v140, v140, v12, v28
	v_fma_f32 v141, v141, v13, v29
	v_fma_f32 v142, v142, v14, v30
	v_fma_f32 v143, v143, v15, v31
	v_fma_f32 v144, v144, v16, v32
	v_fma_f32 v145, v145, v17, v33
	v_fma_f32 v146, v146, v18, v34
	v_fma_f32 v147, v147, v19, v35
	v_fma_f32 v148, v148, v20, v36
	v_fma_f32 v149, v149, v21, v37
	v_fma_f32 v150, v150, v22, v38
	v_fma_f32 v151, v151, v23, v39
	v_add_u32_e32 v171, 0x2400000, v1
	global_store_dwordx4 v171, v[136:139], s[4:5]
	global_store_dwordx4 v171, v[140:143], s[4:5] offset:1024
	global_store_dwordx4 v171, v[144:147], s[4:5] offset:2048
	global_store_dwordx4 v171, v[148:151], s[4:5] offset:3072
	s_waitcnt vmcnt(36)
	v_add_f32_e32 v180, v152, v153
	v_add_f32_e32 v181, v156, v157
	v_add_f32_e32 v182, v160, v161
	v_add_f32_e32 v183, v164, v165
	v_add_f32_e32 v180, v180, v154
	v_add_f32_e32 v181, v181, v158
	v_add_f32_e32 v182, v182, v162
	v_add_f32_e32 v183, v183, v166
	v_add_f32_e32 v180, v180, v155
	v_add_f32_e32 v181, v181, v159
	v_add_f32_e32 v182, v182, v163
	v_add_f32_e32 v183, v183, v167
	v_add_f32_e32 v180, v180, v181
	v_add_f32_e32 v182, v182, v183
	v_add_f32_e32 v180, v180, v182
	s_nop 1
	v_add_f32_dpp v180, v180, v180 quad_perm:[1,0,3,2] row_mask:0xf bank_mask:0xf
	s_nop 1
	v_add_f32_dpp v180, v180, v180 quad_perm:[2,3,0,1] row_mask:0xf bank_mask:0xf
	s_nop 1
	v_add_f32_dpp v180, v180, v180 row_half_mirror row_mask:0xf bank_mask:0xf
	s_nop 1
	v_add_f32_dpp v180, v180, v180 row_mirror row_mask:0xf bank_mask:0xf
	s_nop 1
	v_add_f32_dpp v180, v180, v180 row_bcast:15 row_mask:0xa bank_mask:0xf
	s_nop 1
	v_add_f32_dpp v180, v180, v180 row_bcast:31 row_mask:0xc bank_mask:0xf
	s_nop 0
	v_readlane_b32 s20, v180, 63
	s_nop 1
	v_mul_f32_e32 v184, s20, v2
	v_sub_f32_e32 v152, v152, v184
	v_sub_f32_e32 v153, v153, v184
	v_sub_f32_e32 v154, v154, v184
	v_sub_f32_e32 v155, v155, v184
	v_sub_f32_e32 v156, v156, v184
	v_sub_f32_e32 v157, v157, v184
	v_sub_f32_e32 v158, v158, v184
	v_sub_f32_e32 v159, v159, v184
	v_sub_f32_e32 v160, v160, v184
	v_sub_f32_e32 v161, v161, v184
	v_sub_f32_e32 v162, v162, v184
	v_sub_f32_e32 v163, v163, v184
	v_sub_f32_e32 v164, v164, v184
	v_sub_f32_e32 v165, v165, v184
	v_sub_f32_e32 v166, v166, v184
	v_sub_f32_e32 v167, v167, v184
	v_mul_f32_e32 v180, v152, v152
	v_mul_f32_e32 v181, v156, v156
	v_mul_f32_e32 v182, v160, v160
	v_mul_f32_e32 v183, v164, v164
	v_fmac_f32_e32 v180, v153, v153
	v_fmac_f32_e32 v181, v157, v157
	v_fmac_f32_e32 v182, v161, v161
	v_fmac_f32_e32 v183, v165, v165
	v_fmac_f32_e32 v180, v154, v154
	v_fmac_f32_e32 v181, v158, v158
	v_fmac_f32_e32 v182, v162, v162
	v_fmac_f32_e32 v183, v166, v166
	v_fmac_f32_e32 v180, v155, v155
	v_fmac_f32_e32 v181, v159, v159
	v_fmac_f32_e32 v182, v163, v163
	v_fmac_f32_e32 v183, v167, v167
	v_add_f32_e32 v180, v180, v181
	v_add_f32_e32 v182, v182, v183
	v_add_f32_e32 v180, v180, v182
	s_nop 1
	v_add_f32_dpp v180, v180, v180 quad_perm:[1,0,3,2] row_mask:0xf bank_mask:0xf
	s_nop 1
	v_add_f32_dpp v180, v180, v180 quad_perm:[2,3,0,1] row_mask:0xf bank_mask:0xf
	s_nop 1
	v_add_f32_dpp v180, v180, v180 row_half_mirror row_mask:0xf bank_mask:0xf
	s_nop 1
	v_add_f32_dpp v180, v180, v180 row_mirror row_mask:0xf bank_mask:0xf
	s_nop 1
	v_add_f32_dpp v180, v180, v180 row_bcast:15 row_mask:0xa bank_mask:0xf
	s_nop 1
	v_add_f32_dpp v180, v180, v180 row_bcast:31 row_mask:0xc bank_mask:0xf
	s_nop 0
	v_readlane_b32 s20, v180, 63
	s_nop 1
	v_mov_b32_e32 v185, s20
	v_fma_f32 v185, v185, v2, v4
	v_rsq_f32_e32 v185, v185
	s_nop 0
	v_mul_f32_e32 v152, v152, v185
	v_mul_f32_e32 v153, v153, v185
	v_mul_f32_e32 v154, v154, v185
	v_mul_f32_e32 v155, v155, v185
	v_mul_f32_e32 v156, v156, v185
	v_mul_f32_e32 v157, v157, v185
	v_mul_f32_e32 v158, v158, v185
	v_mul_f32_e32 v159, v159, v185
	v_mul_f32_e32 v160, v160, v185
	v_mul_f32_e32 v161, v161, v185
	v_mul_f32_e32 v162, v162, v185
	v_mul_f32_e32 v163, v163, v185
	v_mul_f32_e32 v164, v164, v185
	v_mul_f32_e32 v165, v165, v185
	v_mul_f32_e32 v166, v166, v185
	v_mul_f32_e32 v167, v167, v185
	v_fma_f32 v152, v152, v8, v24
	v_fma_f32 v153, v153, v9, v25
	v_fma_f32 v154, v154, v10, v26
	v_fma_f32 v155, v155, v11, v27
	v_fma_f32 v156, v156, v12, v28
	v_fma_f32 v157, v157, v13, v29
	v_fma_f32 v158, v158, v14, v30
	v_fma_f32 v159, v159, v15, v31
	v_fma_f32 v160, v160, v16, v32
	v_fma_f32 v161, v161, v17, v33
	v_fma_f32 v162, v162, v18, v34
	v_fma_f32 v163, v163, v19, v35
	v_fma_f32 v164, v164, v20, v36
	v_fma_f32 v165, v165, v21, v37
	v_fma_f32 v166, v166, v22, v38
	v_fma_f32 v167, v167, v23, v39
	v_add_u32_e32 v171, 0x2a00000, v1
	global_store_dwordx4 v171, v[152:155], s[4:5]
	global_store_dwordx4 v171, v[156:159], s[4:5] offset:1024
	global_store_dwordx4 v171, v[160:163], s[4:5] offset:2048
	global_store_dwordx4 v171, v[164:167], s[4:5] offset:3072
	s_waitcnt vmcnt(32)
	v_add_f32_e32 v180, v40, v41
	v_add_f32_e32 v181, v44, v45
	v_add_f32_e32 v182, v48, v49
	v_add_f32_e32 v183, v52, v53
	v_add_f32_e32 v180, v180, v42
	v_add_f32_e32 v181, v181, v46
	v_add_f32_e32 v182, v182, v50
	v_add_f32_e32 v183, v183, v54
	v_add_f32_e32 v180, v180, v43
	v_add_f32_e32 v181, v181, v47
	v_add_f32_e32 v182, v182, v51
	v_add_f32_e32 v183, v183, v55
	v_add_f32_e32 v180, v180, v181
	v_add_f32_e32 v182, v182, v183
	v_add_f32_e32 v180, v180, v182
	s_nop 1
	v_add_f32_dpp v180, v180, v180 quad_perm:[1,0,3,2] row_mask:0xf bank_mask:0xf
	s_nop 1
	v_add_f32_dpp v180, v180, v180 quad_perm:[2,3,0,1] row_mask:0xf bank_mask:0xf
	s_nop 1
	v_add_f32_dpp v180, v180, v180 row_half_mirror row_mask:0xf bank_mask:0xf
	s_nop 1
	v_add_f32_dpp v180, v180, v180 row_mirror row_mask:0xf bank_mask:0xf
	s_nop 1
	v_add_f32_dpp v180, v180, v180 row_bcast:15 row_mask:0xa bank_mask:0xf
	s_nop 1
	v_add_f32_dpp v180, v180, v180 row_bcast:31 row_mask:0xc bank_mask:0xf
	s_nop 0
	v_readlane_b32 s20, v180, 63
	s_nop 1
	v_mul_f32_e32 v184, s20, v2
	v_sub_f32_e32 v40, v40, v184
	v_sub_f32_e32 v41, v41, v184
	v_sub_f32_e32 v42, v42, v184
	v_sub_f32_e32 v43, v43, v184
	v_sub_f32_e32 v44, v44, v184
	v_sub_f32_e32 v45, v45, v184
	v_sub_f32_e32 v46, v46, v184
	v_sub_f32_e32 v47, v47, v184
	v_sub_f32_e32 v48, v48, v184
	v_sub_f32_e32 v49, v49, v184
	v_sub_f32_e32 v50, v50, v184
	v_sub_f32_e32 v51, v51, v184
	v_sub_f32_e32 v52, v52, v184
	v_sub_f32_e32 v53, v53, v184
	v_sub_f32_e32 v54, v54, v184
	v_sub_f32_e32 v55, v55, v184
	v_mul_f32_e32 v180, v40, v40
	v_mul_f32_e32 v181, v44, v44
	v_mul_f32_e32 v182, v48, v48
	v_mul_f32_e32 v183, v52, v52
	v_fmac_f32_e32 v180, v41, v41
	v_fmac_f32_e32 v181, v45, v45
	v_fmac_f32_e32 v182, v49, v49
	v_fmac_f32_e32 v183, v53, v53
	v_fmac_f32_e32 v180, v42, v42
	v_fmac_f32_e32 v181, v46, v46
	v_fmac_f32_e32 v182, v50, v50
	v_fmac_f32_e32 v183, v54, v54
	v_fmac_f32_e32 v180, v43, v43
	v_fmac_f32_e32 v181, v47, v47
	v_fmac_f32_e32 v182, v51, v51
	v_fmac_f32_e32 v183, v55, v55
	v_add_f32_e32 v180, v180, v181
	v_add_f32_e32 v182, v182, v183
	v_add_f32_e32 v180, v180, v182
	s_nop 1
	v_add_f32_dpp v180, v180, v180 quad_perm:[1,0,3,2] row_mask:0xf bank_mask:0xf
	s_nop 1
	v_add_f32_dpp v180, v180, v180 quad_perm:[2,3,0,1] row_mask:0xf bank_mask:0xf
	s_nop 1
	v_add_f32_dpp v180, v180, v180 row_half_mirror row_mask:0xf bank_mask:0xf
	s_nop 1
	v_add_f32_dpp v180, v180, v180 row_mirror row_mask:0xf bank_mask:0xf
	s_nop 1
	v_add_f32_dpp v180, v180, v180 row_bcast:15 row_mask:0xa bank_mask:0xf
	s_nop 1
	v_add_f32_dpp v180, v180, v180 row_bcast:31 row_mask:0xc bank_mask:0xf
	s_nop 0
	v_readlane_b32 s20, v180, 63
	s_nop 1
	v_mov_b32_e32 v185, s20
	v_fma_f32 v185, v185, v2, v4
	v_rsq_f32_e32 v185, v185
	s_nop 0
	v_mul_f32_e32 v40, v40, v185
	v_mul_f32_e32 v41, v41, v185
	v_mul_f32_e32 v42, v42, v185
	v_mul_f32_e32 v43, v43, v185
	v_mul_f32_e32 v44, v44, v185
	v_mul_f32_e32 v45, v45, v185
	v_mul_f32_e32 v46, v46, v185
	v_mul_f32_e32 v47, v47, v185
	v_mul_f32_e32 v48, v48, v185
	v_mul_f32_e32 v49, v49, v185
	v_mul_f32_e32 v50, v50, v185
	v_mul_f32_e32 v51, v51, v185
	v_mul_f32_e32 v52, v52, v185
	v_mul_f32_e32 v53, v53, v185
	v_mul_f32_e32 v54, v54, v185
	v_mul_f32_e32 v55, v55, v185
	v_fma_f32 v40, v40, v8, v24
	v_fma_f32 v41, v41, v9, v25
	v_fma_f32 v42, v42, v10, v26
	v_fma_f32 v43, v43, v11, v27
	v_fma_f32 v44, v44, v12, v28
	v_fma_f32 v45, v45, v13, v29
	v_fma_f32 v46, v46, v14, v30
	v_fma_f32 v47, v47, v15, v31
	v_fma_f32 v48, v48, v16, v32
	v_fma_f32 v49, v49, v17, v33
	v_fma_f32 v50, v50, v18, v34
	v_fma_f32 v51, v51, v19, v35
	v_fma_f32 v52, v52, v20, v36
	v_fma_f32 v53, v53, v21, v37
	v_fma_f32 v54, v54, v22, v38
	v_fma_f32 v55, v55, v23, v39
	v_add_u32_e32 v171, 0x3000000, v1
	global_store_dwordx4 v171, v[40:43], s[4:5]
	global_store_dwordx4 v171, v[44:47], s[4:5] offset:1024
	global_store_dwordx4 v171, v[48:51], s[4:5] offset:2048
	global_store_dwordx4 v171, v[52:55], s[4:5] offset:3072
	s_waitcnt vmcnt(28)
	v_add_f32_e32 v180, v56, v57
	v_add_f32_e32 v181, v60, v61
	v_add_f32_e32 v182, v64, v65
	v_add_f32_e32 v183, v68, v69
	v_add_f32_e32 v180, v180, v58
	v_add_f32_e32 v181, v181, v62
	v_add_f32_e32 v182, v182, v66
	v_add_f32_e32 v183, v183, v70
	v_add_f32_e32 v180, v180, v59
	v_add_f32_e32 v181, v181, v63
	v_add_f32_e32 v182, v182, v67
	v_add_f32_e32 v183, v183, v71
	v_add_f32_e32 v180, v180, v181
	v_add_f32_e32 v182, v182, v183
	v_add_f32_e32 v180, v180, v182
	s_nop 1
	v_add_f32_dpp v180, v180, v180 quad_perm:[1,0,3,2] row_mask:0xf bank_mask:0xf
	s_nop 1
	v_add_f32_dpp v180, v180, v180 quad_perm:[2,3,0,1] row_mask:0xf bank_mask:0xf
	s_nop 1
	v_add_f32_dpp v180, v180, v180 row_half_mirror row_mask:0xf bank_mask:0xf
	s_nop 1
	v_add_f32_dpp v180, v180, v180 row_mirror row_mask:0xf bank_mask:0xf
	s_nop 1
	v_add_f32_dpp v180, v180, v180 row_bcast:15 row_mask:0xa bank_mask:0xf
	s_nop 1
	v_add_f32_dpp v180, v180, v180 row_bcast:31 row_mask:0xc bank_mask:0xf
	s_nop 0
	v_readlane_b32 s20, v180, 63
	s_nop 1
	v_mul_f32_e32 v184, s20, v2
	v_sub_f32_e32 v56, v56, v184
	v_sub_f32_e32 v57, v57, v184
	v_sub_f32_e32 v58, v58, v184
	v_sub_f32_e32 v59, v59, v184
	v_sub_f32_e32 v60, v60, v184
	v_sub_f32_e32 v61, v61, v184
	v_sub_f32_e32 v62, v62, v184
	v_sub_f32_e32 v63, v63, v184
	v_sub_f32_e32 v64, v64, v184
	v_sub_f32_e32 v65, v65, v184
	v_sub_f32_e32 v66, v66, v184
	v_sub_f32_e32 v67, v67, v184
	v_sub_f32_e32 v68, v68, v184
	v_sub_f32_e32 v69, v69, v184
	v_sub_f32_e32 v70, v70, v184
	v_sub_f32_e32 v71, v71, v184
	v_mul_f32_e32 v180, v56, v56
	v_mul_f32_e32 v181, v60, v60
	v_mul_f32_e32 v182, v64, v64
	v_mul_f32_e32 v183, v68, v68
	v_fmac_f32_e32 v180, v57, v57
	v_fmac_f32_e32 v181, v61, v61
	v_fmac_f32_e32 v182, v65, v65
	v_fmac_f32_e32 v183, v69, v69
	v_fmac_f32_e32 v180, v58, v58
	v_fmac_f32_e32 v181, v62, v62
	v_fmac_f32_e32 v182, v66, v66
	v_fmac_f32_e32 v183, v70, v70
	v_fmac_f32_e32 v180, v59, v59
	v_fmac_f32_e32 v181, v63, v63
	v_fmac_f32_e32 v182, v67, v67
	v_fmac_f32_e32 v183, v71, v71
	v_add_f32_e32 v180, v180, v181
	v_add_f32_e32 v182, v182, v183
	v_add_f32_e32 v180, v180, v182
	s_nop 1
	v_add_f32_dpp v180, v180, v180 quad_perm:[1,0,3,2] row_mask:0xf bank_mask:0xf
	s_nop 1
	v_add_f32_dpp v180, v180, v180 quad_perm:[2,3,0,1] row_mask:0xf bank_mask:0xf
	s_nop 1
	v_add_f32_dpp v180, v180, v180 row_half_mirror row_mask:0xf bank_mask:0xf
	s_nop 1
	v_add_f32_dpp v180, v180, v180 row_mirror row_mask:0xf bank_mask:0xf
	s_nop 1
	v_add_f32_dpp v180, v180, v180 row_bcast:15 row_mask:0xa bank_mask:0xf
	s_nop 1
	v_add_f32_dpp v180, v180, v180 row_bcast:31 row_mask:0xc bank_mask:0xf
	s_nop 0
	v_readlane_b32 s20, v180, 63
	s_nop 1
	v_mov_b32_e32 v185, s20
	v_fma_f32 v185, v185, v2, v4
	v_rsq_f32_e32 v185, v185
	s_nop 0
	v_mul_f32_e32 v56, v56, v185
	v_mul_f32_e32 v57, v57, v185
	v_mul_f32_e32 v58, v58, v185
	v_mul_f32_e32 v59, v59, v185
	v_mul_f32_e32 v60, v60, v185
	v_mul_f32_e32 v61, v61, v185
	v_mul_f32_e32 v62, v62, v185
	v_mul_f32_e32 v63, v63, v185
	v_mul_f32_e32 v64, v64, v185
	v_mul_f32_e32 v65, v65, v185
	v_mul_f32_e32 v66, v66, v185
	v_mul_f32_e32 v67, v67, v185
	v_mul_f32_e32 v68, v68, v185
	v_mul_f32_e32 v69, v69, v185
	v_mul_f32_e32 v70, v70, v185
	v_mul_f32_e32 v71, v71, v185
	v_fma_f32 v56, v56, v8, v24
	v_fma_f32 v57, v57, v9, v25
	v_fma_f32 v58, v58, v10, v26
	v_fma_f32 v59, v59, v11, v27
	v_fma_f32 v60, v60, v12, v28
	v_fma_f32 v61, v61, v13, v29
	v_fma_f32 v62, v62, v14, v30
	v_fma_f32 v63, v63, v15, v31
	v_fma_f32 v64, v64, v16, v32
	v_fma_f32 v65, v65, v17, v33
	v_fma_f32 v66, v66, v18, v34
	v_fma_f32 v67, v67, v19, v35
	v_fma_f32 v68, v68, v20, v36
	v_fma_f32 v69, v69, v21, v37
	v_fma_f32 v70, v70, v22, v38
	v_fma_f32 v71, v71, v23, v39
	v_add_u32_e32 v171, 0x3600000, v1
	global_store_dwordx4 v171, v[56:59], s[4:5]
	global_store_dwordx4 v171, v[60:63], s[4:5] offset:1024
	global_store_dwordx4 v171, v[64:67], s[4:5] offset:2048
	global_store_dwordx4 v171, v[68:71], s[4:5] offset:3072
	s_branch .Ltr_29
